# GEMM K-loops: LDS-DMA addresses formed on the scalar unit (SGPR base + 32-bit lane offset) instead of 16 64-bit VALU adds per iteration; attention row-sum no-op adds dropped and sub-head-0 Q addresses
# speedup vs baseline: 1.0322x; 1.0074x over previous
; #define PG8_STAGE(bufoff, gbase, voff) do { _Pragma("unroll") for (int _i = 0; _i < 2; ++_i) \
;         __builtin_amdgcn_global_load_lds((const unsigned*)((const char*)(gbase) + (voff)[_i]), (PG8_LAS unsigned*)(lds + (bufoff) + ldsw + _i * 8192), 16, 0, 0); } while (0)
; #define PG8_LDA(dst, b, h) do { _Pragma("unroll") for (int m = 0; m < 4; ++m) _Pragma("unroll") for (int k = 0; k < 2; ++k) dst[m][k] = *(const PG8_LAS bf16x8*)(lds + PG8_SA(b, h) + aoff + m * 2048 + k * 1024); } while (0)
; #define PG8_LDB(dst, b, h) do { _Pragma("unroll") for (int n = 0; n < 2; ++n) _Pragma("unroll") for (int k = 0; k < 2; ++k) dst[n][k] = *(const PG8_LAS bf16x8*)(lds + PG8_SB(b, h) + boff + n * 2048 + k * 1024); } while (0)
; #define PG8_MMA(ai, bj, At, Bt) do { __builtin_amdgcn_s_setprio(1); _Pragma("unroll") for (int m = 0; m < 4; ++m) _Pragma("unroll") for (int n = 0; n < 2; ++n) _Pragma("unroll") for (int k = 0; k < 2; ++k) \
;         acc[ai][bj][m][n] = __builtin_amdgcn_mfma_f32_16x16x32_bf16(Bt[n][k], At[m][k], acc[ai][bj][m][n], 0, 0, 0); __builtin_amdgcn_s_setprio(0); } while (0)
; #define PG8_WAIT_V(n) asm volatile("s_waitcnt vmcnt(" #n ")" ::: "memory")
; #define PG8_WAIT_L(n) asm volatile("s_waitcnt lgkmcnt(" #n ")" ::: "memory")
; #define PG8_BAR __builtin_amdgcn_s_barrier()
; #define PG8_SCHED __builtin_amdgcn_sched_barrier(0)
; template <class Epi, class Sched, bool ALIGN_EPI = false, bool SP2 = false>
; __device__ __forceinline__ void gemm_phase(PG8_LAS unsigned char* lds, const Gemm g, const Sched& S, const Epi& E) {
;     ...
;             PG8_LDB(B0, 0, 0); PG8_LDB(B1, 0, 1); PG8_SCHED; PG8_LDA(At, 0, 0); PG8_STAGE(PG8_SA(1, 1), a1 + hstep, voffA);
;             PG8_WAIT_V(8); PG8_WAIT_L(0); PG8_BAR; PG8_MMA(0, 0, At, B0); PG8_MMA(0, 1, At, B1); PG8_BAR; PG8_SCHED;
;             PG8_LDA(At, 0, 1); PG8_STAGE(PG8_SB(0, 0), b2, voffB); PG8_STAGE(PG8_SB(0, 1), b2 + hstep, voffB); PG8_STAGE(PG8_SA(0, 0), a2, voffA);
;             PG8_WAIT_V(8); PG8_WAIT_L(0); PG8_BAR; PG8_MMA(1, 0, At, B0); PG8_MMA(1, 1, At, B1); PG8_BAR; PG8_SCHED;
.LBB0_119:
	ds_read_b128 v[56:59], v167
	ds_read_b128 v[60:63], v167 offset:1024
	ds_read_b128 v[136:139], v167 offset:2048
	ds_read_b128 v[158:161], v167 offset:3072
	ds_read_b128 v[170:173], v168
	ds_read_b128 v[174:177], v168 offset:1024
	ds_read_b128 v[178:181], v168 offset:2048
	ds_read_b128 v[182:185], v168 offset:3072
	s_add_u32 s26, s24, 0xfffc0080
	s_addc_u32 s27, s25, -1
	s_cmp_eq_u32 s50, 12
	s_cselect_b32 s29, s5, s27
	s_cselect_b32 s28, s7, s26
	s_cselect_b32 s27, s17, s37
	s_cselect_b32 s26, s19, s36
	s_add_u32 vcc_lo, s26, 0x80
	s_addc_u32 vcc_hi, s27, 0
	s_add_u32 s100, s28, 0x80
	s_addc_u32 s101, s29, 0
	s_add_i32 m0, s31, 0xc000
	ds_read_b128 v[186:189], v169
	ds_read_b128 v[194:197], v169 offset:1024
	ds_read_b128 v[198:201], v169 offset:2048
	ds_read_b128 v[202:205], v169 offset:3072
	ds_read_b128 v[206:209], v169 offset:4096
	ds_read_b128 v[210:213], v169 offset:5120
	ds_read_b128 v[214:217], v169 offset:6144
	ds_read_b128 v[218:221], v169 offset:7168
	global_load_lds_dwordx4 v150, s[24:25]
	s_add_i32 m0, s31, 0xe000
	s_nop 0
	global_load_lds_dwordx4 v152, s[24:25]
	s_waitcnt vmcnt(8)
	s_waitcnt lgkmcnt(0)
	s_barrier
	s_setprio 1
	s_waitcnt lgkmcnt(0)
	v_mfma_f32_16x16x32_bf16 v[132:135], v[56:59], v[186:189], v[132:135]
	v_mfma_f32_16x16x32_bf16 v[128:131], v[136:139], v[186:189], v[128:131]
	v_mfma_f32_16x16x32_bf16 v[116:119], v[56:59], v[198:201], v[116:119]
	v_mfma_f32_16x16x32_bf16 v[112:115], v[136:139], v[198:201], v[112:115]
	v_mfma_f32_16x16x32_bf16 v[100:103], v[56:59], v[206:209], v[100:103]
	v_mfma_f32_16x16x32_bf16 v[96:99], v[136:139], v[206:209], v[96:99]
	v_mfma_f32_16x16x32_bf16 v[84:87], v[56:59], v[214:217], v[84:87]
	v_mfma_f32_16x16x32_bf16 v[80:83], v[136:139], v[214:217], v[80:83]
	v_mfma_f32_16x16x32_bf16 v[132:135], v[60:63], v[194:197], v[132:135]
	v_mfma_f32_16x16x32_bf16 v[128:131], v[158:161], v[194:197], v[128:131]
	v_mfma_f32_16x16x32_bf16 v[116:119], v[60:63], v[202:205], v[116:119]
	v_mfma_f32_16x16x32_bf16 v[112:115], v[158:161], v[202:205], v[112:115]
	v_mfma_f32_16x16x32_bf16 v[100:103], v[60:63], v[210:213], v[100:103]
	v_mfma_f32_16x16x32_bf16 v[96:99], v[158:161], v[210:213], v[96:99]
	v_mfma_f32_16x16x32_bf16 v[84:87], v[60:63], v[218:221], v[84:87]
	v_mfma_f32_16x16x32_bf16 v[80:83], v[158:161], v[218:221], v[80:83]
	s_setprio 0
	s_setprio 1
	v_mfma_f32_16x16x32_bf16 v[124:127], v[170:173], v[186:189], v[124:127]
	v_mfma_f32_16x16x32_bf16 v[120:123], v[178:181], v[186:189], v[120:123]
	v_mfma_f32_16x16x32_bf16 v[108:111], v[170:173], v[198:201], v[108:111]
	v_mfma_f32_16x16x32_bf16 v[104:107], v[178:181], v[198:201], v[104:107]
	v_mfma_f32_16x16x32_bf16 v[92:95], v[170:173], v[206:209], v[92:95]
	v_mfma_f32_16x16x32_bf16 v[88:91], v[178:181], v[206:209], v[88:91]
	v_mfma_f32_16x16x32_bf16 v[76:79], v[170:173], v[214:217], v[76:79]
	v_mfma_f32_16x16x32_bf16 v[72:75], v[178:181], v[214:217], v[72:75]
	v_mfma_f32_16x16x32_bf16 v[124:127], v[174:177], v[194:197], v[124:127]
	v_mfma_f32_16x16x32_bf16 v[120:123], v[182:185], v[194:197], v[120:123]
	v_mfma_f32_16x16x32_bf16 v[108:111], v[174:177], v[202:205], v[108:111]
	v_mfma_f32_16x16x32_bf16 v[104:107], v[182:185], v[202:205], v[104:107]
	v_mfma_f32_16x16x32_bf16 v[92:95], v[174:177], v[210:213], v[92:95]
	v_mfma_f32_16x16x32_bf16 v[88:91], v[182:185], v[210:213], v[88:91]
	v_mfma_f32_16x16x32_bf16 v[76:79], v[174:177], v[218:221], v[76:79]
	v_mfma_f32_16x16x32_bf16 v[72:75], v[182:185], v[218:221], v[72:75]
	s_setprio 0
	s_barrier
	s_add_i32 s51, s88, s58
	s_mov_b32 m0, s51
	ds_read_b128 v[186:189], v169 offset:16384
	ds_read_b128 v[194:197], v169 offset:17408
	ds_read_b128 v[198:201], v169 offset:18432
	ds_read_b128 v[202:205], v169 offset:19456
	ds_read_b128 v[206:209], v169 offset:20480
	ds_read_b128 v[210:213], v169 offset:21504
	ds_read_b128 v[214:217], v169 offset:22528
	ds_read_b128 v[218:221], v169 offset:23552
	global_load_lds_dwordx4 v142, s[26:27]
	s_add_i32 m0, s51, 0x2000
	s_add_u32 s76, s26, 0x40000
	s_addc_u32 s77, s27, 0
	s_add_i32 s51, s89, s58
	global_load_lds_dwordx4 v146, s[26:27]
	s_mov_b32 m0, s51
	s_nop 0
	global_load_lds_dwordx4 v142, s[76:77]
	s_add_i32 m0, s51, 0x2000
	s_nop 0
	global_load_lds_dwordx4 v146, s[76:77]
	s_mov_b32 m0, s31
	s_nop 0
	global_load_lds_dwordx4 v140, s[28:29]
	s_mov_b32 m0, s0
	s_nop 0
	global_load_lds_dwordx4 v144, s[28:29]
	s_waitcnt vmcnt(8)
	s_waitcnt lgkmcnt(0)
	s_barrier
	s_setprio 1
	s_waitcnt lgkmcnt(0)
	v_mfma_f32_16x16x32_bf16 v[68:71], v[56:59], v[186:189], v[68:71]
	v_mfma_f32_16x16x32_bf16 v[64:67], v[136:139], v[186:189], v[64:67]
	v_mfma_f32_16x16x32_bf16 v[44:47], v[56:59], v[198:201], v[44:47]
	v_mfma_f32_16x16x32_bf16 v[40:43], v[136:139], v[198:201], v[40:43]
	v_mfma_f32_16x16x32_bf16 v[28:31], v[56:59], v[206:209], v[28:31]
	v_mfma_f32_16x16x32_bf16 v[24:27], v[136:139], v[206:209], v[24:27]
	v_mfma_f32_16x16x32_bf16 v[12:15], v[56:59], v[214:217], v[12:15]
	v_mfma_f32_16x16x32_bf16 v[8:11], v[136:139], v[214:217], v[8:11]
	v_mfma_f32_16x16x32_bf16 v[68:71], v[60:63], v[194:197], v[68:71]
	v_mfma_f32_16x16x32_bf16 v[64:67], v[158:161], v[194:197], v[64:67]
	v_mfma_f32_16x16x32_bf16 v[44:47], v[60:63], v[202:205], v[44:47]
	v_mfma_f32_16x16x32_bf16 v[40:43], v[158:161], v[202:205], v[40:43]
	v_mfma_f32_16x16x32_bf16 v[28:31], v[60:63], v[210:213], v[28:31]
	v_mfma_f32_16x16x32_bf16 v[24:27], v[158:161], v[210:213], v[24:27]
	v_mfma_f32_16x16x32_bf16 v[12:15], v[60:63], v[218:221], v[12:15]
	v_mfma_f32_16x16x32_bf16 v[8:11], v[158:161], v[218:221], v[8:11]
	s_setprio 0
	s_setprio 1
	v_mfma_f32_16x16x32_bf16 v[52:55], v[170:173], v[186:189], v[52:55]
	v_mfma_f32_16x16x32_bf16 v[48:51], v[178:181], v[186:189], v[48:51]
	v_mfma_f32_16x16x32_bf16 v[36:39], v[170:173], v[198:201], v[36:39]
	v_mfma_f32_16x16x32_bf16 v[32:35], v[178:181], v[198:201], v[32:35]
	v_mfma_f32_16x16x32_bf16 v[20:23], v[170:173], v[206:209], v[20:23]
	v_mfma_f32_16x16x32_bf16 v[16:19], v[178:181], v[206:209], v[16:19]
	v_mfma_f32_16x16x32_bf16 v[4:7], v[170:173], v[214:217], v[4:7]
	v_mfma_f32_16x16x32_bf16 v[0:3], v[178:181], v[214:217], v[0:3]
	v_mfma_f32_16x16x32_bf16 v[52:55], v[174:177], v[194:197], v[52:55]
	v_mfma_f32_16x16x32_bf16 v[48:51], v[182:185], v[194:197], v[48:51]
	v_mfma_f32_16x16x32_bf16 v[36:39], v[174:177], v[202:205], v[36:39]
	v_mfma_f32_16x16x32_bf16 v[32:35], v[182:185], v[202:205], v[32:35]
	v_mfma_f32_16x16x32_bf16 v[20:23], v[174:177], v[210:213], v[20:23]
	v_mfma_f32_16x16x32_bf16 v[16:19], v[182:185], v[210:213], v[16:19]
	v_mfma_f32_16x16x32_bf16 v[4:7], v[174:177], v[218:221], v[4:7]
	v_mfma_f32_16x16x32_bf16 v[0:3], v[182:185], v[218:221], v[0:3]
	s_setprio 0
	s_barrier
; #define PG8_STAGE(bufoff, gbase, voff) do { _Pragma("unroll") for (int _i = 0; _i < 2; ++_i) \
;         __builtin_amdgcn_global_load_lds((const unsigned*)((const char*)(gbase) + (voff)[_i]), (PG8_LAS unsigned*)(lds + (bufoff) + ldsw + _i * 8192), 16, 0, 0); } while (0)
; #define PG8_LDA(dst, b, h) do { _Pragma("unroll") for (int m = 0; m < 4; ++m) _Pragma("unroll") for (int k = 0; k < 2; ++k) dst[m][k] = *(const PG8_LAS bf16x8*)(lds + PG8_SA(b, h) + aoff + m * 2048 + k * 1024); } while (0)
; #define PG8_LDB(dst, b, h) do { _Pragma("unroll") for (int n = 0; n < 2; ++n) _Pragma("unroll") for (int k = 0; k < 2; ++k) dst[n][k] = *(const PG8_LAS bf16x8*)(lds + PG8_SB(b, h) + boff + n * 2048 + k * 1024); } while (0)
; #define PG8_MMA(ai, bj, At, Bt) do { __builtin_amdgcn_s_setprio(1); _Pragma("unroll") for (int m = 0; m < 4; ++m) _Pragma("unroll") for (int n = 0; n < 2; ++n) _Pragma("unroll") for (int k = 0; k < 2; ++k) \
;         acc[ai][bj][m][n] = __builtin_amdgcn_mfma_f32_16x16x32_bf16(Bt[n][k], At[m][k], acc[ai][bj][m][n], 0, 0, 0); __builtin_amdgcn_s_setprio(0); } while (0)
; #define PG8_WAIT_V(n) asm volatile("s_waitcnt vmcnt(" #n ")" ::: "memory")
; #define PG8_WAIT_L(n) asm volatile("s_waitcnt lgkmcnt(" #n ")" ::: "memory")
; #define PG8_BAR __builtin_amdgcn_s_barrier()
; #define PG8_SCHED __builtin_amdgcn_sched_barrier(0)
; template <class Epi, class Sched, bool ALIGN_EPI = false, bool SP2 = false>
; __device__ __forceinline__ void gemm_phase(PG8_LAS unsigned char* lds, const Gemm g, const Sched& S, const Epi& E) {
;     ...
;             PG8_LDB(B0, 1, 0); PG8_LDB(B1, 1, 1); PG8_SCHED; PG8_LDA(At, 1, 0); PG8_STAGE(PG8_SA(0, 1), a2 + hstep, voffA);
;             PG8_WAIT_V(8); PG8_WAIT_L(0); PG8_BAR; PG8_MMA(0, 0, At, B0); PG8_MMA(0, 1, At, B1); PG8_BAR; PG8_SCHED;
;             PG8_LDA(At, 1, 1); PG8_STAGE(PG8_SB(1, 0), b3, voffB); PG8_STAGE(PG8_SB(1, 1), b3 + hstep, voffB); PG8_STAGE(PG8_SA(1, 0), a3, voffA);
;             PG8_WAIT_V(8); PG8_WAIT_L(0); PG8_BAR; PG8_MMA(1, 0, At, B0); PG8_MMA(1, 1, At, B1); PG8_BAR; PG8_SCHED;
	s_add_i32 s51, 0, 0x18000
	s_add_i32 s76, 0, 0x1c000
	v_add_u32_e32 v158, s51, v165
	v_add_u32_e32 v182, s76, v165
	ds_read_b128 v[56:59], v158
	ds_read_b128 v[60:63], v158 offset:1024
	ds_read_b128 v[136:139], v158 offset:2048
	ds_read_b128 v[158:161], v158 offset:3072
	ds_read_b128 v[170:173], v182
	ds_read_b128 v[174:177], v182 offset:1024
	ds_read_b128 v[178:181], v182 offset:2048
	ds_read_b128 v[182:185], v182 offset:3072
	s_add_u32 s28, s28, 0x40000
	s_addc_u32 s29, s29, 0
	s_mov_b32 m0, s1
	ds_read_b128 v[186:189], v169 offset:32768
	ds_read_b128 v[194:197], v169 offset:33792
	ds_read_b128 v[198:201], v169 offset:34816
	ds_read_b128 v[202:205], v169 offset:35840
	ds_read_b128 v[206:209], v169 offset:36864
	ds_read_b128 v[210:213], v169 offset:37888
	ds_read_b128 v[214:217], v169 offset:38912
	ds_read_b128 v[218:221], v169 offset:39936
	global_load_lds_dwordx4 v140, s[28:29]
	s_mov_b32 m0, s38
	s_nop 0
	global_load_lds_dwordx4 v144, s[28:29]
	s_waitcnt vmcnt(8)
	s_waitcnt lgkmcnt(0)
	s_barrier
	s_setprio 1
	s_waitcnt lgkmcnt(0)
	v_mfma_f32_16x16x32_bf16 v[132:135], v[56:59], v[186:189], v[132:135]
	v_mfma_f32_16x16x32_bf16 v[128:131], v[136:139], v[186:189], v[128:131]
	v_mfma_f32_16x16x32_bf16 v[116:119], v[56:59], v[198:201], v[116:119]
	v_mfma_f32_16x16x32_bf16 v[112:115], v[136:139], v[198:201], v[112:115]
	v_mfma_f32_16x16x32_bf16 v[100:103], v[56:59], v[206:209], v[100:103]
	v_mfma_f32_16x16x32_bf16 v[96:99], v[136:139], v[206:209], v[96:99]
	v_mfma_f32_16x16x32_bf16 v[84:87], v[56:59], v[214:217], v[84:87]
	v_mfma_f32_16x16x32_bf16 v[80:83], v[136:139], v[214:217], v[80:83]
	v_mfma_f32_16x16x32_bf16 v[132:135], v[60:63], v[194:197], v[132:135]
	v_mfma_f32_16x16x32_bf16 v[128:131], v[158:161], v[194:197], v[128:131]
	v_mfma_f32_16x16x32_bf16 v[116:119], v[60:63], v[202:205], v[116:119]
	v_mfma_f32_16x16x32_bf16 v[112:115], v[158:161], v[202:205], v[112:115]
	v_mfma_f32_16x16x32_bf16 v[100:103], v[60:63], v[210:213], v[100:103]
	v_mfma_f32_16x16x32_bf16 v[96:99], v[158:161], v[210:213], v[96:99]
	v_mfma_f32_16x16x32_bf16 v[84:87], v[60:63], v[218:221], v[84:87]
	v_mfma_f32_16x16x32_bf16 v[80:83], v[158:161], v[218:221], v[80:83]
	s_setprio 0
	s_setprio 1
	v_mfma_f32_16x16x32_bf16 v[124:127], v[170:173], v[186:189], v[124:127]
	v_mfma_f32_16x16x32_bf16 v[120:123], v[178:181], v[186:189], v[120:123]
	v_mfma_f32_16x16x32_bf16 v[108:111], v[170:173], v[198:201], v[108:111]
	v_mfma_f32_16x16x32_bf16 v[104:107], v[178:181], v[198:201], v[104:107]
	v_mfma_f32_16x16x32_bf16 v[92:95], v[170:173], v[206:209], v[92:95]
	v_mfma_f32_16x16x32_bf16 v[88:91], v[178:181], v[206:209], v[88:91]
	v_mfma_f32_16x16x32_bf16 v[76:79], v[170:173], v[214:217], v[76:79]
	v_mfma_f32_16x16x32_bf16 v[72:75], v[178:181], v[214:217], v[72:75]
	v_mfma_f32_16x16x32_bf16 v[124:127], v[174:177], v[194:197], v[124:127]
	v_mfma_f32_16x16x32_bf16 v[120:123], v[182:185], v[194:197], v[120:123]
	v_mfma_f32_16x16x32_bf16 v[108:111], v[174:177], v[202:205], v[108:111]
	v_mfma_f32_16x16x32_bf16 v[104:107], v[182:185], v[202:205], v[104:107]
	v_mfma_f32_16x16x32_bf16 v[92:95], v[174:177], v[210:213], v[92:95]
	v_mfma_f32_16x16x32_bf16 v[88:91], v[182:185], v[210:213], v[88:91]
	v_mfma_f32_16x16x32_bf16 v[76:79], v[174:177], v[218:221], v[76:79]
	v_mfma_f32_16x16x32_bf16 v[72:75], v[182:185], v[218:221], v[72:75]
	s_setprio 0
	s_barrier
	s_add_i32 s28, s51, s58
	s_mov_b32 m0, s28
	ds_read_b128 v[186:189], v169 offset:49152
	ds_read_b128 v[194:197], v169 offset:50176
	ds_read_b128 v[198:201], v169 offset:51200
	ds_read_b128 v[202:205], v169 offset:52224
	ds_read_b128 v[206:209], v169 offset:53248
	ds_read_b128 v[210:213], v169 offset:54272
	ds_read_b128 v[214:217], v169 offset:55296
	ds_read_b128 v[218:221], v169 offset:56320
	global_load_lds_dwordx4 v142, vcc
	s_add_i32 m0, s28, 0x2000
	s_add_u32 s26, s26, 0x40080
	s_addc_u32 s27, s27, 0
	s_add_i32 s28, s76, s58
	global_load_lds_dwordx4 v146, vcc
	s_mov_b32 m0, s28
	s_nop 0
	global_load_lds_dwordx4 v142, s[26:27]
	s_add_i32 m0, s28, 0x2000
	s_nop 0
	global_load_lds_dwordx4 v146, s[26:27]
	s_mov_b32 m0, s42
	s_nop 0
	global_load_lds_dwordx4 v140, s[100:101]
	s_mov_b32 m0, s59
	s_nop 0
	global_load_lds_dwordx4 v144, s[100:101]
	s_waitcnt vmcnt(8)
	s_waitcnt lgkmcnt(0)
	s_barrier
	s_setprio 1
	s_waitcnt lgkmcnt(0)
	v_mfma_f32_16x16x32_bf16 v[68:71], v[56:59], v[186:189], v[68:71]
	v_mfma_f32_16x16x32_bf16 v[64:67], v[136:139], v[186:189], v[64:67]
	v_mfma_f32_16x16x32_bf16 v[44:47], v[56:59], v[198:201], v[44:47]
	v_mfma_f32_16x16x32_bf16 v[40:43], v[136:139], v[198:201], v[40:43]
	v_mfma_f32_16x16x32_bf16 v[28:31], v[56:59], v[206:209], v[28:31]
	v_mfma_f32_16x16x32_bf16 v[24:27], v[136:139], v[206:209], v[24:27]
	v_mfma_f32_16x16x32_bf16 v[12:15], v[56:59], v[214:217], v[12:15]
	v_mfma_f32_16x16x32_bf16 v[8:11], v[136:139], v[214:217], v[8:11]
	v_mfma_f32_16x16x32_bf16 v[68:71], v[60:63], v[194:197], v[68:71]
	v_mfma_f32_16x16x32_bf16 v[64:67], v[158:161], v[194:197], v[64:67]
	v_mfma_f32_16x16x32_bf16 v[44:47], v[60:63], v[202:205], v[44:47]
	v_mfma_f32_16x16x32_bf16 v[40:43], v[158:161], v[202:205], v[40:43]
	v_mfma_f32_16x16x32_bf16 v[28:31], v[60:63], v[210:213], v[28:31]
	v_mfma_f32_16x16x32_bf16 v[24:27], v[158:161], v[210:213], v[24:27]
	v_mfma_f32_16x16x32_bf16 v[12:15], v[60:63], v[218:221], v[12:15]
	v_mfma_f32_16x16x32_bf16 v[8:11], v[158:161], v[218:221], v[8:11]
	s_setprio 0
	s_setprio 1
	v_mfma_f32_16x16x32_bf16 v[52:55], v[170:173], v[186:189], v[52:55]
	v_mfma_f32_16x16x32_bf16 v[48:51], v[178:181], v[186:189], v[48:51]
	v_mfma_f32_16x16x32_bf16 v[36:39], v[170:173], v[198:201], v[36:39]
	v_mfma_f32_16x16x32_bf16 v[32:35], v[178:181], v[198:201], v[32:35]
	v_mfma_f32_16x16x32_bf16 v[20:23], v[170:173], v[206:209], v[20:23]
	v_mfma_f32_16x16x32_bf16 v[16:19], v[178:181], v[206:209], v[16:19]
	v_mfma_f32_16x16x32_bf16 v[4:7], v[170:173], v[214:217], v[4:7]
	v_mfma_f32_16x16x32_bf16 v[0:3], v[178:181], v[214:217], v[0:3]
	v_mfma_f32_16x16x32_bf16 v[52:55], v[174:177], v[194:197], v[52:55]
	v_mfma_f32_16x16x32_bf16 v[48:51], v[182:185], v[194:197], v[48:51]
	v_mfma_f32_16x16x32_bf16 v[36:39], v[174:177], v[202:205], v[36:39]
	v_mfma_f32_16x16x32_bf16 v[32:35], v[182:185], v[202:205], v[32:35]
	v_mfma_f32_16x16x32_bf16 v[20:23], v[174:177], v[210:213], v[20:23]
	v_mfma_f32_16x16x32_bf16 v[16:19], v[182:185], v[210:213], v[16:19]
	v_mfma_f32_16x16x32_bf16 v[4:7], v[174:177], v[218:221], v[4:7]
	v_mfma_f32_16x16x32_bf16 v[0:3], v[182:185], v[218:221], v[0:3]
	s_setprio 0
	s_barrier
	s_add_i32 s50, s50, 2
	s_add_u32 s24, s24, 0x100
	s_addc_u32 s25, s25, 0
	s_add_u32 s36, s36, 0x100
	s_addc_u32 s37, s37, 0
	s_cmp_gt_u32 s50, 13
	s_cbranch_scc0 .LBB0_119
	s_and_b64 vcc, exec, s[12:13]
	s_cbranch_vccz .LBB0_122
	s_barrier

; #define ATT_LAS __attribute__((address_space(3)))
; #define ATT_STAGE(t, buf) do { _Pragma("unroll") for (int i_ = 0; i_ < 2; ++i_) { \
;         glds16(Kt + (size_t)(t) * 131072, ksrc[i_], (unsigned)__builtin_amdgcn_readfirstlane(ldsb + KBUF + (buf) * 16384 + (w * 2 + i_) * 1024)); \
;         glds16(Vt + (size_t)(t) * 131072, vsrc[i_], (unsigned)__builtin_amdgcn_readfirstlane(ldsb + VBUF + (buf) * 16384 + (w * 2 + i_) * 1024)); } } while (0)
; __device__ __forceinline__ void attn_unit(ATT_LAS unsigned char* lds, const bf16_t* Qg, const bf16_t* Kg, const bf16_t* Vg, bf16_t* Og, int b, int head, int qb, float lam, const float* subg) {
;     int tid = threadIdx.x; asm volatile("" : "+v"(tid));
;     const int lane = tid & 63, r = lane & 31, h = lane >> 5;
;     const int w = __builtin_amdgcn_readfirstlane(tid >> 6);
;     const size_t rowbase = (size_t)b * SEQ; const int q0 = qb * 256, NT = (q0 + 256) >> 6;
;     const int wq = (w < 4) ? w : 11 - w;
;     const char* Kt = (const char*)(Kg + rowbase * PITCH + head * 128);
;     const char* Vt = (const char*)(Vg + rowbase * PITCH + head * 128);
;     unsigned ksrc[2], vsrc[2];
; #pragma unroll
;     for (int i = 0; i < 2; ++i) { const int ii = w * 2 + i;
;         { const int row = 4 * ii + (lane >> 4), pc = lane & 15; ksrc[i] = (unsigned)(row * 2048 + ((pc ^ (row & 15)) << 4)); }
;         { const int row = 8 * (ii >> 1) + ((lane >> 2) & 7), ch = 4 * (2 * (ii & 1) + (lane >> 5)) + ((lane & 3) ^ ((row >> 2) & 3)); vsrc[i] = (unsigned)(row * 2048 + ch * 16); } }
;     const unsigned ldsb = (unsigned)(uintptr_t)lds;
;     ...
;     ATT_STAGE(0, 0);
;     { const char* Qw = (const char*)(Qg + (rowbase + q0 + wq * 32) * PITCH + head * 128);
; #pragma unroll
;       for (int i = 0; i < 8; ++i) { const int row = 4 * i + (lane >> 4), pc = lane & 15;
;           glds16(Qw, (unsigned)(row * 2048 + ((pc ^ (row & 15)) << 4)), (unsigned)__builtin_amdgcn_readfirstlane(ldsb + QBUF + w * 8192 + i * 1024)); } }
;     const ATT_LAS unsigned char* qbase = lds + QBUF + w * 8192;
;     int kaddr[4], vaddr[2];
; #pragma unroll
;     for (int ds = 0; ds < 4; ++ds) kaddr[ds] = koffs(r, 2 * ds + h);
;     { const int q = (lane & 15) >> 2, p = lane & 3, blk = (lane >> 4) & 1;
; #pragma unroll
;       for (int sub = 0; sub < 2; ++sub) vaddr[sub] = voffs(8 * sub + 4 * h + q, 2 * blk + (p >> 1)) + 8 * (p & 1); }
.LBB0_285:
	s_mov_b32 s100, 0x42800000
	v_mov_b32_e32 v0, v190
	s_xor_b64 s[88:89], s[2:3], -1
	v_readfirstlane_b32 s4, v0
	s_ashr_i32 s4, s4, 6
	s_and_b64 s[2:3], s[2:3], exec
	s_cselect_b32 s5, s1, s0
	s_lshl_b32 s3, s4, 3
	v_lshrrev_b32_e32 v5, 2, v0
	v_and_or_b32 v5, v5, 7, s3
	v_bfe_u32 v3, v0, 4, 2
	v_lshrrev_b32_e32 v6, 2, v5
	v_or_b32_e32 v4, s3, v3
	v_xor_b32_e32 v6, v6, v0
	v_bitop3_b32 v8, s3, v0, v3 bitop3:0x36
	v_bfe_u32 v195, v0, 5, 1
	v_lshlrev_b32_e32 v7, 11, v4
	v_lshlrev_b32_e32 v8, 4, v8
	v_lshlrev_b32_e32 v6, 4, v6
	s_lshl_b32 s77, s4, 11
	s_add_i32 s2, s5, 0x100
	v_lshlrev_b32_e32 v5, 11, v5
	v_and_or_b32 v198, v8, s97, v7
	v_lshlrev_b32_e32 v7, 6, v195
	v_and_b32_e32 v6, 48, v6
	s_add_i32 s6, 0, 0x8000
	s_or_b32 s50, s77, 0x400
	s_lshr_b32 s76, s2, 6
	s_sub_i32 s2, 11, s4
	v_or3_b32 v199, v6, v7, v5
	v_or_b32_e32 v5, 4, v4
	v_bitop3_b32 v4, v4, v0, 4 bitop3:0x36
	s_add_i32 s3, s77, 0
	s_add_i32 s7, s77, s6
	s_add_i32 s8, s50, 0
	s_add_i32 s6, s50, s6
	s_mov_b32 s9, m0
	s_mov_b32 m0, s3
	s_nop 0
	global_load_lds_dwordx4 v198, s[64:65]
	s_mov_b32 m0, s9
	v_lshlrev_b32_e32 v5, 11, v5
	v_lshlrev_b32_e32 v4, 4, v4
	s_cmp_lt_i32 s4, 4
	s_mov_b32 s3, m0
	s_mov_b32 m0, s7
	s_nop 0
	global_load_lds_dwordx4 v199, s[66:67]
	s_mov_b32 m0, s3
	v_and_or_b32 v200, v4, s97, v5
	s_mov_b32 s3, m0
	s_mov_b32 m0, s8
	s_nop 0
	global_load_lds_dwordx4 v200, s[64:65]
	s_mov_b32 m0, s3
	s_cselect_b32 s2, s4, s2
	v_or_b32_e32 v201, 0x80, v199
	s_mov_b32 s3, m0
	s_mov_b32 m0, s6
	s_nop 0
	global_load_lds_dwordx4 v201, s[66:67]
	s_mov_b32 m0, s3
	s_lshl_b32 s6, s2, 5
	s_or_b32 s3, s68, s5
	s_ashr_i32 s7, s6, 31
	s_add_u32 s2, s3, s6
	s_addc_u32 s3, s69, s7
	s_lshl_b64 s[90:91], s[2:3], 10
	s_lshl_b64 s[2:3], s[2:3], 11
	s_add_u32 s2, s48, s2
	v_xor_b32_e32 v5, v3, v0
	s_addc_u32 s3, s49, s3
	v_lshlrev_b32_e32 v4, 11, v3
	v_lshlrev_b32_e32 v5, 4, v5
	s_add_u32 s2, s2, s42
	v_and_or_b32 v4, v5, s97, v4
	v_or_b32_e32 v5, 4, v3
	v_bitop3_b32 v6, v3, v0, 4 bitop3:0x36
	s_addc_u32 s3, s3, 0
	s_lshl_b32 s7, s4, 13
	v_lshlrev_b32_e32 v5, 11, v5
	v_lshlrev_b32_e32 v6, 4, v6
	s_add_i32 s51, s7, s99
	s_mov_b32 s8, m0
	s_mov_b32 m0, s51
	s_nop 0
	global_load_lds_dwordx4 v4, s[2:3]
	s_mov_b32 m0, s8
	v_and_or_b32 v5, v6, s97, v5
	s_add_i32 s7, s7, 0
	s_add_i32 s8, s7, 0x11400
	s_mov_b32 s9, m0
	s_mov_b32 m0, s8
	s_nop 0
	global_load_lds_dwordx4 v5, s[2:3]
	s_mov_b32 m0, s9
	v_or_b32_e32 v5, 8, v3
	v_bitop3_b32 v6, v3, v0, 8 bitop3:0x36
	v_lshlrev_b32_e32 v5, 11, v5
	v_lshlrev_b32_e32 v6, 4, v6
	v_and_or_b32 v5, v6, s97, v5
	s_add_i32 s8, s7, 0x11800
	s_mov_b32 s9, m0
	s_mov_b32 m0, s8
	s_nop 0
	global_load_lds_dwordx4 v5, s[2:3]
	s_mov_b32 m0, s9
	v_or_b32_e32 v5, 12, v3
	v_bitop3_b32 v6, v3, v0, 12 bitop3:0x36
	v_lshlrev_b32_e32 v5, 11, v5
	v_lshlrev_b32_e32 v6, 4, v6
	v_and_or_b32 v5, v6, s97, v5
	s_add_i32 s8, s7, 0x11c00
	s_mov_b32 s9, m0
	s_mov_b32 m0, s8
	s_nop 0
	global_load_lds_dwordx4 v5, s[2:3]
	s_mov_b32 m0, s9
	v_or_b32_e32 v4, 0x8000, v4
	s_add_i32 s8, s7, 0x12000
	s_mov_b32 s9, m0
	s_mov_b32 m0, s8
	s_nop 0
	global_load_lds_dwordx4 v4, s[2:3]
	s_mov_b32 m0, s9
	v_or_b32_e32 v4, 20, v3
	v_bitop3_b32 v5, v3, v0, 20 bitop3:0x36
	v_lshlrev_b32_e32 v4, 11, v4
	v_lshlrev_b32_e32 v5, 4, v5
	v_and_or_b32 v4, v5, s97, v4
	s_add_i32 s8, s7, 0x12400
	s_mov_b32 s9, m0
	s_mov_b32 m0, s8
	s_nop 0
	global_load_lds_dwordx4 v4, s[2:3]
	s_mov_b32 m0, s9
	v_or_b32_e32 v4, 24, v3
	v_bitop3_b32 v5, v3, v0, 24 bitop3:0x36
	v_lshlrev_b32_e32 v4, 11, v4
	v_lshlrev_b32_e32 v5, 4, v5
	v_and_or_b32 v4, v5, s97, v4
	s_add_i32 s8, s7, 0x12800
	s_mov_b32 s9, m0
	s_mov_b32 m0, s8
	s_nop 0
	global_load_lds_dwordx4 v4, s[2:3]
	s_mov_b32 m0, s9
	v_or_b32_e32 v4, 28, v3
	v_bitop3_b32 v3, v3, v0, 28 bitop3:0x36
	v_lshrrev_b32_e32 v8, 3, v0
	v_lshlrev_b32_e32 v4, 11, v4
	v_lshlrev_b32_e32 v3, 4, v3
	v_and_b32_e32 v8, 2, v8
	v_bfe_u32 v9, v0, 1, 1
	v_lshlrev_b32_e32 v11, 4, v0
	v_and_b32_e32 v2, 63, v0
	v_and_b32_e32 v196, 31, v0
	v_and_or_b32 v3, v3, s97, v4
	v_and_b32_e32 v4, 15, v0
	v_bitop3_b32 v5, v195, v0, 15 bitop3:0x78
	v_or_b32_e32 v10, v8, v9
	v_and_b32_e32 v11, 0xc0, v11
	v_lshlrev_b32_e32 v0, 3, v0
	v_bitop3_b32 v8, v8, v195, v9 bitop3:0x36
	v_lshl_or_b32 v11, v195, 8, v11
	v_and_b32_e32 v0, 8, v0
	v_lshlrev_b32_e32 v8, 4, v8
	v_or3_b32 v207, v8, v11, v0
	v_bitop3_b32 v8, v195, v10, 2 bitop3:0x36
	s_add_i32 s7, s7, 0x12c00
	s_mov_b32 s8, m0
	s_mov_b32 m0, s7
	s_nop 0
	global_load_lds_dwordx4 v3, s[2:3]
	s_mov_b32 m0, s8
	v_bitop3_b32 v6, v195, v4, 2 bitop3:0x36
	v_bitop3_b32 v7, v195, v4, 4 bitop3:0x36
	v_bitop3_b32 v4, v195, v4, 6 bitop3:0x36
	v_lshlrev_b32_e32 v8, 4, v8
	s_lshl_b32 s2, s4, 9
	s_add_i32 s5, s5, s6
	v_lshlrev_b32_e32 v3, 8, v196
	v_lshlrev_b32_e32 v5, 4, v5
	v_lshlrev_b32_e32 v6, 4, v6
	v_lshlrev_b32_e32 v7, 4, v7
	v_lshlrev_b32_e32 v4, 4, v4
	s_add_i32 s78, s2, 0
	s_waitcnt vmcnt(0)
; #define ATT_LAS __attribute__((address_space(3)))
; __device__ __forceinline__ void attn_unit(ATT_LAS unsigned char* lds, const bf16_t* Qg, const bf16_t* Kg, const bf16_t* Vg, bf16_t* Og, int b, int head, int qb, float lam, const float* subg) {
;     ...
;     const ATT_LAS unsigned char* qbase = lds + QBUF + w * 8192;
;     int kaddr[4], vaddr[2];
; #pragma unroll
;     for (int ds = 0; ds < 4; ++ds) kaddr[ds] = koffs(r, 2 * ds + h);
;     { const int q = (lane & 15) >> 2, p = lane & 3, blk = (lane >> 4) & 1;
; #pragma unroll
;       for (int sub = 0; sub < 2; ++sub) vaddr[sub] = voffs(8 * sub + 4 * h + q, 2 * blk + (p >> 1)) + 8 * (p & 1); }
;     ATT_LAS float* wsf = (ATT_LAS float*)(lds + WSF + w * 512);
;     f32x16 O1[4], O2[4];
; #pragma unroll
;     for (int db = 0; db < 4; ++db)
; #pragma unroll
;         for (int i = 0; i < 16; ++i) { O1[db][i] = 0.f; O2[db][i] = 0.f; }
;     float m1 = -1e30f, m2 = -1e30f, l1 = 0.f, l2 = 0.f;
;     asm volatile("s_waitcnt vmcnt(0)" ::: "memory"); __syncthreads();
	v_lshlrev_b32_e32 v197, 2, v195
	v_or3_b32 v213, v8, v11, v0
	v_add_u32_e32 v0, s5, v196
	v_mov_b32_e32 v14, v1
	v_mov_b32_e32 v15, v1
	v_or_b32_e32 v203, v5, v3
	v_or_b32_e32 v204, v6, v3
	v_or_b32_e32 v205, v7, v3
	v_or_b32_e32 v206, v4, v3
	s_add_i32 s78, s78, 0x10000
	v_cmp_gt_u32_e64 s[2:3], 32, v2
	v_bitop3_b32 v209, v5, s98, v3 bitop3:0x36
	v_bitop3_b32 v210, v6, s98, v3 bitop3:0x36
	v_bitop3_b32 v211, v7, s98, v3 bitop3:0x36
	v_bitop3_b32 v212, v4, s98, v3 bitop3:0x36
	v_add_u32_e32 v244, s51, v209
	v_add_u32_e32 v245, s51, v210
	v_add_u32_e32 v246, s51, v211
	v_add_u32_e32 v247, s51, v212
	v_add_u32_e32 v217, s51, v203
	v_add_u32_e32 v219, s51, v204
	v_add_u32_e32 v221, s51, v205
	v_add_u32_e32 v223, s51, v206
	v_sub_u32_e32 v214, v0, v197
	v_mov_b32_e32 v0, v1
	v_mov_b32_e32 v2, v1
	v_mov_b32_e32 v3, v1
	v_mov_b32_e32 v4, v1
	v_mov_b32_e32 v5, v1
	v_mov_b32_e32 v6, v1
	v_mov_b32_e32 v7, v1
	v_mov_b32_e32 v8, v1
	v_mov_b32_e32 v9, v1
	v_mov_b32_e32 v10, v1
	v_mov_b32_e32 v11, v1
	v_mov_b32_e32 v12, v1
	v_mov_b32_e32 v13, v1
	v_mov_b64_e32 v[32:33], v[14:15]
	v_mov_b64_e32 v[112:113], v[14:15]
	v_mov_b64_e32 v[128:129], v[14:15]
	v_mov_b64_e32 v[144:145], v[14:15]
	v_mov_b64_e32 v[48:49], v[14:15]
	v_mov_b64_e32 v[64:65], v[14:15]
	v_mov_b64_e32 v[80:81], v[14:15]
	v_mov_b64_e32 v[96:97], v[14:15]
	v_lshl_add_u32 v202, v196, 2, s78
	v_lshlrev_b32_e32 v208, 4, v195
	s_mov_b32 s79, 0
	s_sub_i32 s80, 0, s5
	v_mov_b32_e32 v215, 0xf149f2ca
	v_mov_b32_e32 v224, 0
	s_mov_b64 s[92:93], s[86:87]
	s_mov_b64 s[94:95], s[70:71]
	v_mov_b64_e32 v[30:31], v[12:13]
	v_mov_b64_e32 v[28:29], v[10:11]
	v_mov_b64_e32 v[26:27], v[8:9]
	v_mov_b64_e32 v[24:25], v[6:7]
	v_mov_b64_e32 v[22:23], v[4:5]
	v_mov_b64_e32 v[20:21], v[2:3]
	v_mov_b64_e32 v[18:19], v[0:1]
	v_mov_b64_e32 v[110:111], v[12:13]
	v_mov_b64_e32 v[108:109], v[10:11]
	v_mov_b64_e32 v[106:107], v[8:9]
	v_mov_b64_e32 v[104:105], v[6:7]
	v_mov_b64_e32 v[102:103], v[4:5]
	v_mov_b64_e32 v[100:101], v[2:3]
	v_mov_b64_e32 v[98:99], v[0:1]
	v_mov_b64_e32 v[126:127], v[12:13]
	v_mov_b64_e32 v[124:125], v[10:11]
	v_mov_b64_e32 v[122:123], v[8:9]
	v_mov_b64_e32 v[120:121], v[6:7]
	v_mov_b64_e32 v[118:119], v[4:5]
	v_mov_b64_e32 v[116:117], v[2:3]
	v_mov_b64_e32 v[114:115], v[0:1]
	v_mov_b64_e32 v[142:143], v[12:13]
	v_mov_b64_e32 v[140:141], v[10:11]
	v_mov_b64_e32 v[138:139], v[8:9]
	v_mov_b64_e32 v[136:137], v[6:7]
	v_mov_b64_e32 v[134:135], v[4:5]
	v_mov_b64_e32 v[132:133], v[2:3]
	v_mov_b64_e32 v[130:131], v[0:1]
	v_mov_b64_e32 v[46:47], v[12:13]
	v_mov_b64_e32 v[44:45], v[10:11]
	v_mov_b64_e32 v[42:43], v[8:9]
	v_mov_b64_e32 v[40:41], v[6:7]
	v_mov_b64_e32 v[38:39], v[4:5]
	v_mov_b64_e32 v[36:37], v[2:3]
	v_mov_b64_e32 v[34:35], v[0:1]
	v_mov_b64_e32 v[62:63], v[12:13]
	v_mov_b64_e32 v[60:61], v[10:11]
	v_mov_b64_e32 v[58:59], v[8:9]
	v_mov_b64_e32 v[56:57], v[6:7]
	v_mov_b64_e32 v[54:55], v[4:5]
	v_mov_b64_e32 v[52:53], v[2:3]
	v_mov_b64_e32 v[50:51], v[0:1]
	v_mov_b64_e32 v[78:79], v[12:13]
	v_mov_b64_e32 v[76:77], v[10:11]
	v_mov_b64_e32 v[74:75], v[8:9]
	v_mov_b64_e32 v[72:73], v[6:7]
	v_mov_b64_e32 v[70:71], v[4:5]
	v_mov_b64_e32 v[68:69], v[2:3]
	v_mov_b64_e32 v[66:67], v[0:1]
	v_mov_b64_e32 v[94:95], v[12:13]
	v_mov_b64_e32 v[92:93], v[10:11]
	v_mov_b64_e32 v[90:91], v[8:9]
	v_mov_b64_e32 v[88:89], v[6:7]
	v_mov_b64_e32 v[86:87], v[4:5]
	v_mov_b64_e32 v[84:85], v[2:3]
	v_mov_b64_e32 v[82:83], v[0:1]
	v_mov_b32_e32 v225, 0
	v_mov_b32_e32 v0, 0xf149f2ca
	s_barrier
	s_branch .LBB0_289

; #define ATT_LAS __attribute__((address_space(3)))
; __device__ __forceinline__ int sub1(int a) { int v = a ^ 128; asm volatile("" : "+v"(v)); return v; }
; #define ATT_MFMA(a, b, c) __builtin_amdgcn_mfma_f32_32x32x16_bf16((a), (b), (c), 0, 0, 0)
; template <bool C1> __device__ __forceinline__ void qk_issue(f32x16& s0, const ATT_LAS unsigned char* kb, const ATT_LAS unsigned char* qb_, const int (&kaddr)[4]) {
; #pragma unroll
;     for (int i = 0; i < 16; ++i) s0[i] = 0.f;
; #pragma unroll
;     for (int ds = 0; ds < 4; ++ds) {
;         const int ad = C1 ? sub1(kaddr[ds]) : kaddr[ds];
;         const bf16x8 a0 = *(const ATT_LAS bf16x8*)(kb + ad);
;         const bf16x8 qv = *(const ATT_LAS bf16x8*)(qb_ + ad);
;         s0 = ATT_MFMA(a0, qv, s0);
;     }
; }
; __device__ __forceinline__ void apply_mask(bool MASK, f32x16& s0, int kvr, int r, int h) {
;     if (MASK) {
;         asm volatile("" ::: "memory");
;         const int d = r - 4 * h - kvr;
; #pragma unroll
;         for (int i = 0; i < 16; ++i) { if (((i & 3) + 8 * (i >> 2)) > d) s0[i] = -INFINITY; }
;     }
; }
.LBB0_291:
	s_cmp_gt_i32 s80, 31
	s_cbranch_scc1 .LBB0_288
	s_lshl_b32 s4, s4, 14
	s_add_i32 s81, s4, 0
	v_add_u32_e32 v248, s81, v209
	v_add_u32_e32 v249, s81, v210
	v_add_u32_e32 v250, s81, v211
	v_add_u32_e32 v251, s81, v212
	v_add_u32_e32 v216, s81, v203
	ds_read_b128 v[2:5], v216
	ds_read_b128 v[6:9], v217
	v_add_u32_e32 v218, s81, v204
	v_add_u32_e32 v220, s81, v205
	v_add_u32_e32 v222, s81, v206
	s_waitcnt lgkmcnt(0)
	v_mfma_f32_32x32x16_bf16 v[170:185], v[2:5], v[6:9], 0
	ds_read_b128 v[2:5], v218
	ds_read_b128 v[6:9], v219
	s_cmpk_gt_i32 s80, 0xffc1
	s_cselect_b64 s[36:37], -1, 0
	s_cmpk_lt_i32 s80, 0xffc2
	v_cmp_gt_i32_e32 vcc, 26, v214
	s_waitcnt lgkmcnt(0)
	v_mfma_f32_32x32x16_bf16 v[170:185], v[2:5], v[6:9], v[170:185]
	ds_read_b128 v[2:5], v220
	ds_read_b128 v[6:9], v221
	s_waitcnt lgkmcnt(0)
	v_mfma_f32_32x32x16_bf16 v[170:185], v[2:5], v[6:9], v[170:185]
	ds_read_b128 v[2:5], v222
	ds_read_b128 v[6:9], v223
	s_waitcnt lgkmcnt(0)
	v_mfma_f32_32x32x16_bf16 v[170:185], v[2:5], v[6:9], v[170:185]
	s_cbranch_scc1 .LBB0_296
	v_cmp_gt_i32_e64 s[34:35], 25, v214
	v_cmp_gt_i32_e64 s[28:29], 24, v214
	s_and_b64 s[34:35], vcc, s[34:35]
	v_cmp_gt_i32_e64 s[26:27], 19, v214
	s_and_b64 s[28:29], s[34:35], s[28:29]
	v_cmp_gt_i32_e64 s[24:25], 18, v214
	s_and_b64 s[26:27], s[28:29], s[26:27]
	v_cmp_gt_i32_e64 s[22:23], 17, v214
	s_and_b64 s[24:25], s[26:27], s[24:25]
	v_cmp_gt_i32_e64 s[20:21], 16, v214
	s_and_b64 s[22:23], s[24:25], s[22:23]
	v_cmp_gt_i32_e64 s[18:19], 11, v214
	s_and_b64 s[20:21], s[22:23], s[20:21]
	v_cmp_gt_i32_e64 s[16:17], 10, v214
	s_and_b64 s[18:19], s[20:21], s[18:19]
	v_cmp_gt_i32_e64 s[14:15], 9, v214
	s_and_b64 s[16:17], s[18:19], s[16:17]
	v_cmp_gt_i32_e64 s[12:13], 8, v214
	s_and_b64 s[14:15], s[16:17], s[14:15]
	v_cmp_gt_i32_e64 s[10:11], 3, v214
	s_and_b64 s[12:13], s[14:15], s[12:13]
	v_cmp_gt_i32_e64 s[8:9], 2, v214
	s_and_b64 s[10:11], s[12:13], s[10:11]
	v_cmp_gt_i32_e64 s[6:7], 1, v214
	s_and_b64 s[8:9], s[10:11], s[8:9]
	v_cmp_gt_i32_e64 s[4:5], 0, v214
	s_and_b64 s[6:7], s[8:9], s[6:7]
	s_and_b64 s[4:5], s[6:7], s[4:5]
	v_cndmask_b32_e64 v183, v183, v17, s[34:35]
	v_cndmask_b32_e64 v182, v182, v17, s[28:29]
	v_cndmask_b32_e64 v181, v181, v17, s[26:27]
	v_cndmask_b32_e64 v180, v180, v17, s[24:25]
	v_cndmask_b32_e64 v179, v179, v17, s[22:23]
	v_cndmask_b32_e64 v178, v178, v17, s[20:21]
	v_cndmask_b32_e64 v177, v177, v17, s[18:19]
	v_cndmask_b32_e64 v176, v176, v17, s[16:17]
	v_cndmask_b32_e64 v175, v175, v17, s[14:15]
	v_cndmask_b32_e64 v174, v174, v17, s[12:13]
	v_cndmask_b32_e64 v173, v173, v17, s[10:11]
	v_cndmask_b32_e64 v172, v172, v17, s[8:9]
	v_cndmask_b32_e64 v171, v171, v17, s[6:7]
	v_cndmask_b32_e64 v170, v170, v17, s[4:5]
	v_cndmask_b32_e32 v184, v184, v17, vcc
	v_cmp_gt_i32_e32 vcc, 27, v214
	s_and_saveexec_b64 s[4:5], vcc
	v_mov_b32_e32 v185, s31
	s_or_b64 exec, exec, s[4:5]

; #define ATT_LAS __attribute__((address_space(3)))
; __device__ __forceinline__ unsigned cvtpk(float lo, float hi) { unsigned r; asm volatile("v_cvt_pk_bf16_f32 %0, %1, %2" : "=v"(r) : "v"(lo), "v"(hi)); return r; }
; template <bool HAS_PV, bool HAS_QK, bool C1> ...
;     s16x4 vlo[2], vhi[2]; bf16x8 ka, qa;
;     if (HAS_PV) {
; #pragma unroll
;         for (int u = 0; u < 2; ++u) { vlo[u] = vtr(vb + vaddr[0] + u * 512); vhi[u] = vtr(vb + vaddr[1] + u * 512); } }
;     if (HAS_QK) { const int ad = C1 ? sub1(kaddr[0]) : kaddr[0]; ka = *(const ATT_LAS bf16x8*)(kb + ad); qa = *(const ATT_LAS bf16x8*)(qb_ + ad);
; #pragma unroll
;         for (int i = 0; i < 16; ++i) Snext[i] = 0.f; }
;     float sa = 0.f, sb = 0.f;
; #pragma unroll
;     for (int g = 0; g < 4; ++g) {
;         s16x4 nlo[2], nhi[2]; bf16x8 nk, nq;
;         if (g < 3) {
;             if (HAS_PV) {
; #pragma unroll
;                 for (int u = 0; u < 2; ++u) { const int off = (2 * ((g + 1) & 1) + u) * 512 + ((g + 1) >> 1) * 4096; nlo[u] = vtr(vb + vaddr[0] + off); nhi[u] = vtr(vb + vaddr[1] + off); } }
;             if (HAS_QK) { const int ad = C1 ? sub1(kaddr[g + 1]) : kaddr[g + 1]; nk = *(const ATT_LAS bf16x8*)(kb + ad); nq = *(const ATT_LAS bf16x8*)(qb_ + ad); }
;         }
;         if (HAS_PV) { const bf16x8 pa = __builtin_bit_cast(bf16x8, pkin[g >> 1]);
; #pragma unroll
;             for (int u = 0; u < 2; ++u) { const bf16x8 vf = __builtin_shufflevector(vlo[u], vhi[u], 0, 1, 2, 3, 4, 5, 6, 7); Opv[2 * (g & 1) + u] = ATT_MFMA(pa, vf, Opv[2 * (g & 1) + u]); } }
;         if (HAS_QK) Snext = ATT_MFMA(ka, qa, Snext);
; #pragma unroll
;         for (int e = 4 * g; e < 4 * g + 4; e += 2) { Scur[e] = __builtin_amdgcn_exp2f(Scur[e] - m); Scur[e + 1] = __builtin_amdgcn_exp2f(Scur[e + 1] - m); sa += Scur[e]; sb += Scur[e + 1]; }
;         if (g & 1) pkout[g >> 1] = (u32x4){cvtpk(Scur[4 * g - 4], Scur[4 * g - 3]), cvtpk(Scur[4 * g - 2], Scur[4 * g - 1]), cvtpk(Scur[4 * g], Scur[4 * g + 1]), cvtpk(Scur[4 * g + 2], Scur[4 * g + 3])};
;         if (g < 3) {
;             if (HAS_PV) {
; #pragma unroll
;                 for (int u = 0; u < 2; ++u) { vlo[u] = nlo[u]; vhi[u] = nhi[u]; } }
;             if (HAS_QK) { ka = nk; qa = nq; }
;         }
;         __builtin_amdgcn_sched_barrier(0);
;     }
;     l += sa + sb;
;     return sa + sb;
; }
.Lns_296:
	ds_read_b128 v[2:5], v248
	ds_read_b128 v[6:9], v244
	s_nop 8
	ds_read_b128 v[10:13], v249
	ds_read_b128 v[146:149], v245
	v_exp_f32_e32 v15, v170
	v_mov_b32_e32 v14, v171
	v_exp_f32_e32 v155, v172
	v_mov_b32_e32 v16, v173
	s_waitcnt lgkmcnt(2)
	v_mfma_f32_32x32x16_bf16 v[158:173], v[2:5], v[6:9], 0
	v_exp_f32_e32 v14, v14
	v_exp_f32_e32 v154, v16
	s_waitcnt lgkmcnt(0)
	v_mfma_f32_32x32x16_bf16 v[158:173], v[10:13], v[146:149], v[158:173]
	ds_read_b128 v[6:9], v250
	ds_read_b128 v[150:153], v246
	v_exp_f32_e32 v157, v174
	v_exp_f32_e32 v156, v175
	v_exp_f32_e32 v175, v176
	v_exp_f32_e32 v174, v177
	v_cvt_pk_bf16_f32 v2, v15, v14
	v_cvt_pk_bf16_f32 v3, v155, v154
	v_cvt_pk_bf16_f32 v4, v157, v156
	v_cvt_pk_bf16_f32 v5, v175, v174
	s_waitcnt lgkmcnt(0)
	v_mfma_f32_32x32x16_bf16 v[158:173], v[6:9], v[150:153], v[158:173]
	ds_read_b128 v[10:13], v251
	ds_read_b128 v[146:149], v247
	v_exp_f32_e32 v177, v178
	v_exp_f32_e32 v176, v179
	v_exp_f32_e32 v179, v180
	v_exp_f32_e32 v178, v181
	s_waitcnt lgkmcnt(0)
	v_mfma_f32_32x32x16_bf16 v[158:173], v[10:13], v[146:149], v[158:173]
	v_exp_f32_e32 v7, v182
	v_pk_add_f32 v[14:15], v[154:155], v[14:15]
	v_exp_f32_e32 v6, v183
	v_exp_f32_e32 v9, v184
	v_pk_add_f32 v[14:15], v[156:157], v[14:15]
	v_exp_f32_e32 v8, v185
	v_pk_add_f32 v[14:15], v[174:175], v[14:15]
	v_cvt_pk_bf16_f32 v10, v177, v176
	v_cvt_pk_bf16_f32 v11, v179, v178
	v_cvt_pk_bf16_f32 v12, v7, v6
	v_cvt_pk_bf16_f32 v13, v9, v8
	s_nop 0
	v_pk_add_f32 v[14:15], v[176:177], v[14:15]
	s_nop 0
	v_pk_add_f32 v[14:15], v[178:179], v[14:15]
	s_nop 0
	v_pk_add_f32 v[6:7], v[6:7], v[14:15]
	s_nop 0
	v_pk_add_f32 v[6:7], v[8:9], v[6:7]
	s_nop 0
	v_add_f32_e32 v6, v6, v7
	v_cndmask_b32_e64 v7, 0, 1, s[36:37]
	v_cmp_nge_f32_e32 vcc, s58, v6
	v_cmp_ne_u32_e64 s[4:5], 1, v7
	s_cbranch_vccz .Lns_305
	s_branch .Lslow_1

; #define ATT_LAS __attribute__((address_space(3)))
; __device__ __forceinline__ unsigned cvtpk(float lo, float hi) { unsigned r; asm volatile("v_cvt_pk_bf16_f32 %0, %1, %2" : "=v"(r) : "v"(lo), "v"(hi)); return r; }
; template <bool HAS_PV, bool HAS_QK, bool C1> ...
;     s16x4 vlo[2], vhi[2]; bf16x8 ka, qa;
;     if (HAS_PV) {
; #pragma unroll
;         for (int u = 0; u < 2; ++u) { vlo[u] = vtr(vb + vaddr[0] + u * 512); vhi[u] = vtr(vb + vaddr[1] + u * 512); } }
;     if (HAS_QK) { const int ad = C1 ? sub1(kaddr[0]) : kaddr[0]; ka = *(const ATT_LAS bf16x8*)(kb + ad); qa = *(const ATT_LAS bf16x8*)(qb_ + ad);
; #pragma unroll
;         for (int i = 0; i < 16; ++i) Snext[i] = 0.f; }
;     float sa = 0.f, sb = 0.f;
; #pragma unroll
;     for (int g = 0; g < 4; ++g) {
;         s16x4 nlo[2], nhi[2]; bf16x8 nk, nq;
;         if (g < 3) {
;             if (HAS_PV) {
; #pragma unroll
;                 for (int u = 0; u < 2; ++u) { const int off = (2 * ((g + 1) & 1) + u) * 512 + ((g + 1) >> 1) * 4096; nlo[u] = vtr(vb + vaddr[0] + off); nhi[u] = vtr(vb + vaddr[1] + off); } }
;             if (HAS_QK) { const int ad = C1 ? sub1(kaddr[g + 1]) : kaddr[g + 1]; nk = *(const ATT_LAS bf16x8*)(kb + ad); nq = *(const ATT_LAS bf16x8*)(qb_ + ad); }
;         }
;         if (HAS_PV) { const bf16x8 pa = __builtin_bit_cast(bf16x8, pkin[g >> 1]);
; #pragma unroll
;             for (int u = 0; u < 2; ++u) { const bf16x8 vf = __builtin_shufflevector(vlo[u], vhi[u], 0, 1, 2, 3, 4, 5, 6, 7); Opv[2 * (g & 1) + u] = ATT_MFMA(pa, vf, Opv[2 * (g & 1) + u]); } }
;         if (HAS_QK) Snext = ATT_MFMA(ka, qa, Snext);
; #pragma unroll
;         for (int e = 4 * g; e < 4 * g + 4; e += 2) { Scur[e] = __builtin_amdgcn_exp2f(Scur[e] - m); Scur[e + 1] = __builtin_amdgcn_exp2f(Scur[e + 1] - m); sa += Scur[e]; sb += Scur[e + 1]; }
;         if (g & 1) pkout[g >> 1] = (u32x4){cvtpk(Scur[4 * g - 4], Scur[4 * g - 3]), cvtpk(Scur[4 * g - 2], Scur[4 * g - 1]), cvtpk(Scur[4 * g], Scur[4 * g + 1]), cvtpk(Scur[4 * g + 2], Scur[4 * g + 3])};
;         if (g < 3) {
;             if (HAS_PV) {
; #pragma unroll
;                 for (int u = 0; u < 2; ++u) { vlo[u] = nlo[u]; vhi[u] = nhi[u]; } }
;             if (HAS_QK) { ka = nk; qa = nq; }
;         }
;         __builtin_amdgcn_sched_barrier(0);
;     }
;     l += sa + sb;
;     return sa + sb;
; }
.Lns_311:
	v_add_u32_e32 v178, s81, v213
	v_add_u32_e32 v179, s81, v207
	ds_read_b64_tr_b16 v[8:9], v178 offset:34816
	ds_read_b64_tr_b16 v[6:7], v179 offset:32768
	ds_read_b64_tr_b16 v[146:147], v179 offset:33280
	ds_read_b64_tr_b16 v[174:175], v179 offset:33792
	ds_read_b64_tr_b16 v[182:183], v179 offset:34304
	ds_read_b64_tr_b16 v[148:149], v178 offset:35328
	ds_read_b64_tr_b16 v[176:177], v178 offset:35840
	ds_read_b64_tr_b16 v[184:185], v178 offset:36352
	s_waitcnt lgkmcnt(6)
	v_mfma_f32_32x32x16_bf16 v[34:49], v[2:5], v[6:9], v[34:49]
	ds_read_b128 v[6:9], v216 offset:8192
	ds_read_b128 v[150:153], v217
	ds_read_b128 v[186:189], v218 offset:8192
	ds_read_b128 v[226:229], v219
	v_exp_f32_e32 v15, v158
	v_exp_f32_e32 v239, v160
	s_waitcnt lgkmcnt(6)
	v_mfma_f32_32x32x16_bf16 v[50:65], v[2:5], v[146:149], v[50:65]
	v_exp_f32_e32 v14, v159
	v_exp_f32_e32 v238, v161
	s_waitcnt lgkmcnt(2)
	v_mfma_f32_32x32x16_bf16 v[146:161], v[6:9], v[150:153], 0
	v_mfma_f32_32x32x16_bf16 v[66:81], v[2:5], v[174:177], v[66:81]
	ds_read_b64_tr_b16 v[6:7], v179 offset:36864
	ds_read_b64_tr_b16 v[8:9], v178 offset:38912
	ds_read_b64_tr_b16 v[176:177], v178 offset:39424
	ds_read_b64_tr_b16 v[174:175], v179 offset:37376
	ds_read_b128 v[230:233], v220 offset:8192
	ds_read_b128 v[234:237], v221
	v_exp_f32_e32 v241, v162
	v_exp_f32_e32 v240, v163
	v_mfma_f32_32x32x16_bf16 v[82:97], v[2:5], v[182:185], v[82:97]
	v_exp_f32_e32 v243, v164
	v_exp_f32_e32 v242, v165
	v_cvt_pk_bf16_f32 v2, v15, v14
	v_cvt_pk_bf16_f32 v3, v239, v238
	v_cvt_pk_bf16_f32 v4, v241, v240
	s_waitcnt lgkmcnt(6)
	v_mfma_f32_32x32x16_bf16 v[146:161], v[186:189], v[226:229], v[146:161]
	v_cvt_pk_bf16_f32 v5, v243, v242
	s_waitcnt lgkmcnt(4)
	v_mfma_f32_32x32x16_bf16 v[34:49], v[10:13], v[6:9], v[34:49]
	ds_read_b64_tr_b16 v[6:7], v179 offset:37888
	ds_read_b64_tr_b16 v[8:9], v178 offset:39936
	ds_read_b64_tr_b16 v[164:165], v178 offset:40448
	ds_read_b64_tr_b16 v[162:163], v179 offset:38400
	ds_read_b128 v[182:185], v222 offset:8192
	ds_read_b128 v[186:189], v223
	s_waitcnt lgkmcnt(8)
	v_mfma_f32_32x32x16_bf16 v[50:65], v[10:13], v[174:177], v[50:65]
	v_exp_f32_e32 v175, v166
	v_exp_f32_e32 v174, v167
	v_exp_f32_e32 v167, v168
	v_exp_f32_e32 v166, v169
	s_waitcnt lgkmcnt(6)
	v_mfma_f32_32x32x16_bf16 v[146:161], v[230:233], v[234:237], v[146:161]
	s_waitcnt lgkmcnt(4)
	v_mfma_f32_32x32x16_bf16 v[66:81], v[10:13], v[6:9], v[66:81]
	v_exp_f32_e32 v169, v170
	v_exp_f32_e32 v168, v171
	v_exp_f32_e32 v171, v172
	v_exp_f32_e32 v170, v173
	s_waitcnt lgkmcnt(2)
	v_mfma_f32_32x32x16_bf16 v[82:97], v[10:13], v[162:165], v[82:97]
	v_cvt_pk_bf16_f32 v6, v175, v174
	v_cvt_pk_bf16_f32 v7, v167, v166
	v_cvt_pk_bf16_f32 v8, v169, v168
	v_cvt_pk_bf16_f32 v9, v171, v170
	v_add_f32_e64 v10, v238, v14
	v_add_f32_e64 v11, v239, v15
	s_waitcnt lgkmcnt(0)
	v_mfma_f32_32x32x16_bf16 v[146:161], v[182:185], v[186:189], v[146:161]
	v_add_f32_e64 v10, v240, v10
	v_add_f32_e64 v11, v241, v11
	v_add_f32_e64 v10, v242, v10
	v_add_f32_e64 v11, v243, v11
	v_add_f32_e64 v10, v174, v10
	v_add_f32_e64 v11, v175, v11
	v_pk_add_f32 v[10:11], v[166:167], v[10:11]
	s_nop 0
	v_pk_add_f32 v[10:11], v[168:169], v[10:11]
	s_nop 0
	v_pk_add_f32 v[10:11], v[170:171], v[10:11]
	s_nop 0
	v_add_f32_e32 v10, v10, v11
	v_cmp_nge_f32_e32 vcc, s58, v10
	s_cbranch_vccz .Lns_320
	s_branch .Lslow_2

; #define ATT_LAS __attribute__((address_space(3)))
; __device__ __forceinline__ unsigned cvtpk(float lo, float hi) { unsigned r; asm volatile("v_cvt_pk_bf16_f32 %0, %1, %2" : "=v"(r) : "v"(lo), "v"(hi)); return r; }
; template <bool HAS_PV, bool HAS_QK, bool C1> ...
;     s16x4 vlo[2], vhi[2]; bf16x8 ka, qa;
;     if (HAS_PV) {
; #pragma unroll
;         for (int u = 0; u < 2; ++u) { vlo[u] = vtr(vb + vaddr[0] + u * 512); vhi[u] = vtr(vb + vaddr[1] + u * 512); } }
;     if (HAS_QK) { const int ad = C1 ? sub1(kaddr[0]) : kaddr[0]; ka = *(const ATT_LAS bf16x8*)(kb + ad); qa = *(const ATT_LAS bf16x8*)(qb_ + ad);
; #pragma unroll
;         for (int i = 0; i < 16; ++i) Snext[i] = 0.f; }
;     float sa = 0.f, sb = 0.f;
; #pragma unroll
;     for (int g = 0; g < 4; ++g) {
;         s16x4 nlo[2], nhi[2]; bf16x8 nk, nq;
;         if (g < 3) {
;             if (HAS_PV) {
; #pragma unroll
;                 for (int u = 0; u < 2; ++u) { const int off = (2 * ((g + 1) & 1) + u) * 512 + ((g + 1) >> 1) * 4096; nlo[u] = vtr(vb + vaddr[0] + off); nhi[u] = vtr(vb + vaddr[1] + off); } }
;             if (HAS_QK) { const int ad = C1 ? sub1(kaddr[g + 1]) : kaddr[g + 1]; nk = *(const ATT_LAS bf16x8*)(kb + ad); nq = *(const ATT_LAS bf16x8*)(qb_ + ad); }
;         }
;         if (HAS_PV) { const bf16x8 pa = __builtin_bit_cast(bf16x8, pkin[g >> 1]);
; #pragma unroll
;             for (int u = 0; u < 2; ++u) { const bf16x8 vf = __builtin_shufflevector(vlo[u], vhi[u], 0, 1, 2, 3, 4, 5, 6, 7); Opv[2 * (g & 1) + u] = ATT_MFMA(pa, vf, Opv[2 * (g & 1) + u]); } }
;         if (HAS_QK) Snext = ATT_MFMA(ka, qa, Snext);
; #pragma unroll
;         for (int e = 4 * g; e < 4 * g + 4; e += 2) { Scur[e] = __builtin_amdgcn_exp2f(Scur[e] - m); Scur[e + 1] = __builtin_amdgcn_exp2f(Scur[e + 1] - m); sa += Scur[e]; sb += Scur[e + 1]; }
;         if (g & 1) pkout[g >> 1] = (u32x4){cvtpk(Scur[4 * g - 4], Scur[4 * g - 3]), cvtpk(Scur[4 * g - 2], Scur[4 * g - 1]), cvtpk(Scur[4 * g], Scur[4 * g + 1]), cvtpk(Scur[4 * g + 2], Scur[4 * g + 3])};
;         if (g < 3) {
;             if (HAS_PV) {
; #pragma unroll
;                 for (int u = 0; u < 2; ++u) { vlo[u] = nlo[u]; vhi[u] = nhi[u]; } }
;             if (HAS_QK) { ka = nk; qa = nq; }
;         }
;         __builtin_amdgcn_sched_barrier(0);
;     }
;     l += sa + sb;
;     return sa + sb;
; }
.Lns_326:
	ds_read_b64_tr_b16 v[10:11], v179 offset:32768
	ds_read_b64_tr_b16 v[12:13], v178 offset:34816
	ds_read_b64_tr_b16 v[164:165], v178 offset:35328
	ds_read_b64_tr_b16 v[162:163], v179 offset:33280
	s_waitcnt lgkmcnt(2)
	v_mfma_f32_32x32x16_bf16 v[130:145], v[2:5], v[10:13], v[130:145]
	ds_read_b128 v[166:169], v248 offset:8192
	ds_read_b128 v[170:173], v244
	ds_read_b64_tr_b16 v[10:11], v179 offset:33792
	ds_read_b64_tr_b16 v[12:13], v178 offset:35840
	ds_read_b64_tr_b16 v[184:185], v178 offset:36352
	ds_read_b64_tr_b16 v[182:183], v179 offset:34304
	s_waitcnt lgkmcnt(6)
	v_mfma_f32_32x32x16_bf16 v[114:129], v[2:5], v[162:165], v[114:129]
	ds_read_b128 v[186:189], v249 offset:8192
	ds_read_b128 v[224:227], v245
	v_exp_f32_e32 v15, v146
	v_exp_f32_e32 v237, v148
	s_waitcnt lgkmcnt(6)
	v_mfma_f32_32x32x16_bf16 v[162:177], v[166:169], v[170:173], 0
	v_exp_f32_e32 v14, v147
	v_exp_f32_e32 v236, v149
	s_waitcnt lgkmcnt(4)
	v_mfma_f32_32x32x16_bf16 v[98:113], v[2:5], v[10:13], v[98:113]
	ds_read_b64_tr_b16 v[146:147], v179 offset:36864
	ds_read_b64_tr_b16 v[148:149], v178 offset:38912
	ds_read_b64_tr_b16 v[230:231], v178 offset:39424
	ds_read_b64_tr_b16 v[228:229], v179 offset:37376
	ds_read_b128 v[10:13], v250 offset:8192
	ds_read_b128 v[232:235], v246
	s_waitcnt lgkmcnt(8)
	v_mfma_f32_32x32x16_bf16 v[18:33], v[2:5], v[182:185], v[18:33]
	v_exp_f32_e32 v239, v150
	v_exp_f32_e32 v241, v152
	v_exp_f32_e32 v238, v151
	s_waitcnt lgkmcnt(6)
	v_mfma_f32_32x32x16_bf16 v[162:177], v[186:189], v[224:227], v[162:177]
	v_exp_f32_e32 v240, v153
	v_cvt_pk_bf16_f32 v2, v15, v14
	v_cvt_pk_bf16_f32 v3, v237, v236
	v_cvt_pk_bf16_f32 v4, v239, v238
	v_cvt_pk_bf16_f32 v5, v241, v240
	s_waitcnt lgkmcnt(4)
	v_mfma_f32_32x32x16_bf16 v[130:145], v[6:9], v[146:149], v[130:145]
	ds_read_b64_tr_b16 v[146:147], v179 offset:37888
	ds_read_b64_tr_b16 v[148:149], v178 offset:39936
	ds_read_b64_tr_b16 v[152:153], v178 offset:40448
	ds_read_b64_tr_b16 v[150:151], v179 offset:38400
	ds_read_b128 v[182:185], v251 offset:8192
	ds_read_b128 v[186:189], v247
	s_waitcnt lgkmcnt(8)
	v_mfma_f32_32x32x16_bf16 v[114:129], v[6:9], v[228:231], v[114:129]
	v_exp_f32_e32 v225, v154
	v_exp_f32_e32 v224, v155
	v_exp_f32_e32 v155, v156
	s_waitcnt lgkmcnt(6)
	v_mfma_f32_32x32x16_bf16 v[162:177], v[10:13], v[232:235], v[162:177]
	v_exp_f32_e32 v154, v157
	v_exp_f32_e32 v157, v158
	s_waitcnt lgkmcnt(4)
	v_mfma_f32_32x32x16_bf16 v[98:113], v[6:9], v[146:149], v[98:113]
	v_exp_f32_e32 v156, v159
	v_exp_f32_e32 v147, v160
	v_exp_f32_e32 v146, v161
	v_cvt_pk_bf16_f32 v10, v225, v224
	v_cvt_pk_bf16_f32 v11, v155, v154
	s_waitcnt lgkmcnt(2)
	v_mfma_f32_32x32x16_bf16 v[18:33], v[6:9], v[150:153], v[18:33]
	v_cvt_pk_bf16_f32 v12, v157, v156
	v_cvt_pk_bf16_f32 v13, v147, v146
	v_add_f32_e64 v6, v236, v14
	v_add_f32_e64 v7, v237, v15
	v_add_f32_e64 v6, v238, v6
	v_add_f32_e64 v7, v239, v7
	s_waitcnt lgkmcnt(0)
	v_mfma_f32_32x32x16_bf16 v[162:177], v[182:185], v[186:189], v[162:177]
	v_add_f32_e64 v6, v240, v6
	v_add_f32_e64 v7, v241, v7
	v_add_f32_e64 v6, v224, v6
	v_add_f32_e64 v7, v225, v7
	v_add_f32_e64 v6, v154, v6
	v_add_f32_e64 v7, v155, v7
	v_pk_add_f32 v[6:7], v[156:157], v[6:7]
	s_nop 0
	v_pk_add_f32 v[6:7], v[146:147], v[6:7]
	s_nop 0
	v_add_f32_e32 v6, v6, v7
	v_cmp_nge_f32_e32 vcc, s58, v6
	s_cbranch_vccz .Lns_335
	s_branch .Lslow_3

; #define ATT_LAS __attribute__((address_space(3)))
; __device__ __forceinline__ unsigned cvtpk(float lo, float hi) { unsigned r; asm volatile("v_cvt_pk_bf16_f32 %0, %1, %2" : "=v"(r) : "v"(lo), "v"(hi)); return r; }
; template <bool HAS_PV, bool HAS_QK, bool C1> ...
;     s16x4 vlo[2], vhi[2]; bf16x8 ka, qa;
;     if (HAS_PV) {
; #pragma unroll
;         for (int u = 0; u < 2; ++u) { vlo[u] = vtr(vb + vaddr[0] + u * 512); vhi[u] = vtr(vb + vaddr[1] + u * 512); } }
;     if (HAS_QK) { const int ad = C1 ? sub1(kaddr[0]) : kaddr[0]; ka = *(const ATT_LAS bf16x8*)(kb + ad); qa = *(const ATT_LAS bf16x8*)(qb_ + ad);
; #pragma unroll
;         for (int i = 0; i < 16; ++i) Snext[i] = 0.f; }
;     float sa = 0.f, sb = 0.f;
; #pragma unroll
;     for (int g = 0; g < 4; ++g) {
;         s16x4 nlo[2], nhi[2]; bf16x8 nk, nq;
;         if (g < 3) {
;             if (HAS_PV) {
; #pragma unroll
;                 for (int u = 0; u < 2; ++u) { const int off = (2 * ((g + 1) & 1) + u) * 512 + ((g + 1) >> 1) * 4096; nlo[u] = vtr(vb + vaddr[0] + off); nhi[u] = vtr(vb + vaddr[1] + off); } }
;             if (HAS_QK) { const int ad = C1 ? sub1(kaddr[g + 1]) : kaddr[g + 1]; nk = *(const ATT_LAS bf16x8*)(kb + ad); nq = *(const ATT_LAS bf16x8*)(qb_ + ad); }
;         }
;         if (HAS_PV) { const bf16x8 pa = __builtin_bit_cast(bf16x8, pkin[g >> 1]);
; #pragma unroll
;             for (int u = 0; u < 2; ++u) { const bf16x8 vf = __builtin_shufflevector(vlo[u], vhi[u], 0, 1, 2, 3, 4, 5, 6, 7); Opv[2 * (g & 1) + u] = ATT_MFMA(pa, vf, Opv[2 * (g & 1) + u]); } }
;         if (HAS_QK) Snext = ATT_MFMA(ka, qa, Snext);
; #pragma unroll
;         for (int e = 4 * g; e < 4 * g + 4; e += 2) { Scur[e] = __builtin_amdgcn_exp2f(Scur[e] - m); Scur[e + 1] = __builtin_amdgcn_exp2f(Scur[e + 1] - m); sa += Scur[e]; sb += Scur[e + 1]; }
;         if (g & 1) pkout[g >> 1] = (u32x4){cvtpk(Scur[4 * g - 4], Scur[4 * g - 3]), cvtpk(Scur[4 * g - 2], Scur[4 * g - 1]), cvtpk(Scur[4 * g], Scur[4 * g + 1]), cvtpk(Scur[4 * g + 2], Scur[4 * g + 3])};
;         if (g < 3) {
;             if (HAS_PV) {
; #pragma unroll
;                 for (int u = 0; u < 2; ++u) { vlo[u] = nlo[u]; vhi[u] = nhi[u]; } }
;             if (HAS_QK) { ka = nk; qa = nq; }
;         }
;         __builtin_amdgcn_sched_barrier(0);
;     }
;     l += sa + sb;
;     return sa + sb;
; }
.Lns_341:
	ds_read_b64_tr_b16 v[8:9], v178 offset:43008
	ds_read_b64_tr_b16 v[6:7], v179 offset:40960
	ds_read_b64_tr_b16 v[146:147], v179 offset:41472
	ds_read_b64_tr_b16 v[150:151], v179 offset:41984
	ds_read_b64_tr_b16 v[154:155], v179 offset:42496
	ds_read_b64_tr_b16 v[148:149], v178 offset:43520
	ds_read_b64_tr_b16 v[152:153], v178 offset:44032
	ds_read_b64_tr_b16 v[156:157], v178 offset:44544
	s_waitcnt lgkmcnt(6)
	v_mfma_f32_32x32x16_bf16 v[34:49], v[2:5], v[6:9], v[34:49]
	v_exp_f32_e32 v15, v162
	v_exp_f32_e32 v14, v163
	v_exp_f32_e32 v163, v164
	s_waitcnt lgkmcnt(2)
	v_mfma_f32_32x32x16_bf16 v[50:65], v[2:5], v[146:149], v[50:65]
	v_exp_f32_e32 v162, v165
	s_waitcnt lgkmcnt(1)
	v_mfma_f32_32x32x16_bf16 v[66:81], v[2:5], v[150:153], v[66:81]
	ds_read_b64_tr_b16 v[146:147], v179 offset:45056
	ds_read_b64_tr_b16 v[148:149], v178 offset:47104
	ds_read_b64_tr_b16 v[160:161], v178 offset:47616
	ds_read_b64_tr_b16 v[158:159], v179 offset:45568
	v_exp_f32_e32 v165, v166
	v_exp_f32_e32 v164, v167
	v_exp_f32_e32 v167, v168
	s_waitcnt lgkmcnt(4)
	v_mfma_f32_32x32x16_bf16 v[82:97], v[2:5], v[154:157], v[82:97]
	v_exp_f32_e32 v166, v169
	v_cvt_pk_bf16_f32 v6, v15, v14
	v_cvt_pk_bf16_f32 v7, v163, v162
	v_cvt_pk_bf16_f32 v8, v165, v164
	v_cvt_pk_bf16_f32 v9, v167, v166
	s_waitcnt lgkmcnt(2)
	v_mfma_f32_32x32x16_bf16 v[34:49], v[10:13], v[146:149], v[34:49]
	ds_read_b64_tr_b16 v[2:3], v179 offset:46080
	ds_read_b64_tr_b16 v[4:5], v178 offset:48128
	ds_read_b64_tr_b16 v[152:153], v178 offset:48640
	ds_read_b64_tr_b16 v[150:151], v179 offset:46592
	v_exp_f32_e32 v147, v170
	v_exp_f32_e32 v146, v171
	v_exp_f32_e32 v149, v172
	s_waitcnt lgkmcnt(4)
	v_mfma_f32_32x32x16_bf16 v[50:65], v[10:13], v[158:161], v[50:65]
	v_exp_f32_e32 v148, v173
	s_waitcnt lgkmcnt(2)
	v_mfma_f32_32x32x16_bf16 v[66:81], v[10:13], v[2:5], v[66:81]
	v_exp_f32_e32 v155, v174
	v_exp_f32_e32 v154, v175
	v_exp_f32_e32 v157, v176
	s_waitcnt lgkmcnt(0)
	v_mfma_f32_32x32x16_bf16 v[82:97], v[10:13], v[150:153], v[82:97]
	v_add_f32_e64 v10, v162, v14
	v_add_f32_e64 v11, v163, v15
	v_exp_f32_e32 v156, v177
	v_pk_add_f32 v[10:11], v[164:165], v[10:11]
	v_cvt_pk_bf16_f32 v2, v147, v146
	v_cvt_pk_bf16_f32 v3, v149, v148
	v_cvt_pk_bf16_f32 v4, v155, v154
	v_cvt_pk_bf16_f32 v5, v157, v156
	s_nop 0
	v_pk_add_f32 v[10:11], v[166:167], v[10:11]
	s_nop 0
	v_pk_add_f32 v[10:11], v[146:147], v[10:11]
	s_nop 0
	v_pk_add_f32 v[10:11], v[148:149], v[10:11]
	s_nop 0
	v_pk_add_f32 v[10:11], v[154:155], v[10:11]
	s_nop 0
	v_pk_add_f32 v[10:11], v[156:157], v[10:11]
	s_nop 0
	v_add_f32_e32 v10, v10, v11
	v_cmp_nge_f32_e32 vcc, s58, v10
	s_cbranch_vccz .LBB0_286
	s_branch .Lslow_4

; #define PG8_STAGE(bufoff, gbase, voff) do { _Pragma("unroll") for (int _i = 0; _i < 2; ++_i) \
;         __builtin_amdgcn_global_load_lds((const unsigned*)((const char*)(gbase) + (voff)[_i]), (PG8_LAS unsigned*)(lds + (bufoff) + ldsw + _i * 8192), 16, 0, 0); } while (0)
; #define PG8_LDA(dst, b, h) do { _Pragma("unroll") for (int m = 0; m < 4; ++m) _Pragma("unroll") for (int k = 0; k < 2; ++k) dst[m][k] = *(const PG8_LAS bf16x8*)(lds + PG8_SA(b, h) + aoff + m * 2048 + k * 1024); } while (0)
; #define PG8_LDB(dst, b, h) do { _Pragma("unroll") for (int n = 0; n < 2; ++n) _Pragma("unroll") for (int k = 0; k < 2; ++k) dst[n][k] = *(const PG8_LAS bf16x8*)(lds + PG8_SB(b, h) + boff + n * 2048 + k * 1024); } while (0)
; #define PG8_MMA(ai, bj, At, Bt) do { __builtin_amdgcn_s_setprio(1); _Pragma("unroll") for (int m = 0; m < 4; ++m) _Pragma("unroll") for (int n = 0; n < 2; ++n) _Pragma("unroll") for (int k = 0; k < 2; ++k) \
;         acc[ai][bj][m][n] = __builtin_amdgcn_mfma_f32_16x16x32_bf16(Bt[n][k], At[m][k], acc[ai][bj][m][n], 0, 0, 0); __builtin_amdgcn_s_setprio(0); } while (0)
; #define PG8_WAIT_V(n) asm volatile("s_waitcnt vmcnt(" #n ")" ::: "memory")
; #define PG8_WAIT_L(n) asm volatile("s_waitcnt lgkmcnt(" #n ")" ::: "memory")
; #define PG8_BAR __builtin_amdgcn_s_barrier()
; #define PG8_SCHED __builtin_amdgcn_sched_barrier(0)
; template <class Epi, class Sched, bool ALIGN_EPI = false, bool SP2 = false>
; __device__ __forceinline__ void gemm_phase(PG8_LAS unsigned char* lds, const Gemm g, const Sched& S, const Epi& E) {
;     ...
;             PG8_LDB(B0, 0, 0); PG8_LDB(B1, 0, 1); PG8_SCHED; PG8_LDA(At, 0, 0); PG8_STAGE(PG8_SA(1, 1), a1 + hstep, voffA);
;             PG8_WAIT_V(8); PG8_WAIT_L(0); PG8_BAR; PG8_MMA(0, 0, At, B0); PG8_MMA(0, 1, At, B1); PG8_BAR; PG8_SCHED;
;             PG8_LDA(At, 0, 1); PG8_STAGE(PG8_SB(0, 0), b2, voffB); PG8_STAGE(PG8_SB(0, 1), b2 + hstep, voffB); PG8_STAGE(PG8_SA(0, 0), a2, voffA);
;             PG8_WAIT_V(8); PG8_WAIT_L(0); PG8_BAR; PG8_MMA(1, 0, At, B0); PG8_MMA(1, 1, At, B1); PG8_BAR; PG8_SCHED;
.LBB0_413:
	ds_read_b128 v[144:147], v151
	ds_read_b128 v[154:157], v151 offset:1024
	ds_read_b128 v[158:161], v151 offset:2048
	ds_read_b128 v[162:165], v151 offset:3072
	ds_read_b128 v[166:169], v152
	ds_read_b128 v[170:173], v152 offset:1024
	ds_read_b128 v[174:177], v152 offset:2048
	ds_read_b128 v[178:181], v152 offset:3072
	s_add_u32 s36, s34, 0xfffc0080
	s_addc_u32 s37, s35, -1
	s_cmp_eq_u32 s64, 12
	s_cselect_b32 s41, s23, s37
	s_cselect_b32 s40, s29, s36
	s_cselect_b32 s37, s21, s63
	s_cselect_b32 s36, s59, s62
	s_add_u32 vcc_lo, s36, 0x80
	s_addc_u32 vcc_hi, s37, 0
	s_add_u32 s100, s40, 0x80
	s_addc_u32 s101, s41, 0
	s_add_i32 m0, s1, 0xc000
	ds_read_b128 v[182:185], v153
	ds_read_b128 v[186:189], v153 offset:1024
	ds_read_b128 v[194:197], v153 offset:2048
	ds_read_b128 v[198:201], v153 offset:3072
	ds_read_b128 v[202:205], v153 offset:4096
	ds_read_b128 v[206:209], v153 offset:5120
	ds_read_b128 v[210:213], v153 offset:6144
	ds_read_b128 v[214:217], v153 offset:7168
	global_load_lds_dwordx4 v136, s[34:35]
	s_add_i32 m0, s1, 0xe000
	s_nop 0
	global_load_lds_dwordx4 v138, s[34:35]
	s_waitcnt vmcnt(8)
	s_waitcnt lgkmcnt(0)
	s_barrier
	s_setprio 1
	s_waitcnt lgkmcnt(0)
	v_mfma_f32_16x16x32_bf16 v[124:127], v[144:147], v[182:185], v[124:127]
	v_mfma_f32_16x16x32_bf16 v[120:123], v[158:161], v[182:185], v[120:123]
	v_mfma_f32_16x16x32_bf16 v[108:111], v[144:147], v[194:197], v[108:111]
	v_mfma_f32_16x16x32_bf16 v[104:107], v[158:161], v[194:197], v[104:107]
	v_mfma_f32_16x16x32_bf16 v[92:95], v[144:147], v[202:205], v[92:95]
	v_mfma_f32_16x16x32_bf16 v[88:91], v[158:161], v[202:205], v[88:91]
	v_mfma_f32_16x16x32_bf16 v[76:79], v[144:147], v[210:213], v[76:79]
	v_mfma_f32_16x16x32_bf16 v[72:75], v[158:161], v[210:213], v[72:75]
	v_mfma_f32_16x16x32_bf16 v[124:127], v[154:157], v[186:189], v[124:127]
	v_mfma_f32_16x16x32_bf16 v[120:123], v[162:165], v[186:189], v[120:123]
	v_mfma_f32_16x16x32_bf16 v[108:111], v[154:157], v[198:201], v[108:111]
	v_mfma_f32_16x16x32_bf16 v[104:107], v[162:165], v[198:201], v[104:107]
	v_mfma_f32_16x16x32_bf16 v[92:95], v[154:157], v[206:209], v[92:95]
	v_mfma_f32_16x16x32_bf16 v[88:91], v[162:165], v[206:209], v[88:91]
	v_mfma_f32_16x16x32_bf16 v[76:79], v[154:157], v[214:217], v[76:79]
	v_mfma_f32_16x16x32_bf16 v[72:75], v[162:165], v[214:217], v[72:75]
	s_setprio 0
	s_setprio 1
	v_mfma_f32_16x16x32_bf16 v[116:119], v[166:169], v[182:185], v[116:119]
	v_mfma_f32_16x16x32_bf16 v[112:115], v[174:177], v[182:185], v[112:115]
	v_mfma_f32_16x16x32_bf16 v[100:103], v[166:169], v[194:197], v[100:103]
	v_mfma_f32_16x16x32_bf16 v[96:99], v[174:177], v[194:197], v[96:99]
	v_mfma_f32_16x16x32_bf16 v[84:87], v[166:169], v[202:205], v[84:87]
	v_mfma_f32_16x16x32_bf16 v[80:83], v[174:177], v[202:205], v[80:83]
	v_mfma_f32_16x16x32_bf16 v[68:71], v[166:169], v[210:213], v[68:71]
	v_mfma_f32_16x16x32_bf16 v[64:67], v[174:177], v[210:213], v[64:67]
	v_mfma_f32_16x16x32_bf16 v[116:119], v[170:173], v[186:189], v[116:119]
	v_mfma_f32_16x16x32_bf16 v[112:115], v[178:181], v[186:189], v[112:115]
	v_mfma_f32_16x16x32_bf16 v[100:103], v[170:173], v[198:201], v[100:103]
	v_mfma_f32_16x16x32_bf16 v[96:99], v[178:181], v[198:201], v[96:99]
	v_mfma_f32_16x16x32_bf16 v[84:87], v[170:173], v[206:209], v[84:87]
	v_mfma_f32_16x16x32_bf16 v[80:83], v[178:181], v[206:209], v[80:83]
	v_mfma_f32_16x16x32_bf16 v[68:71], v[170:173], v[214:217], v[68:71]
	v_mfma_f32_16x16x32_bf16 v[64:67], v[178:181], v[214:217], v[64:67]
	s_setprio 0
	s_barrier
	s_add_i32 s65, s50, s0
	s_mov_b32 m0, s65
	ds_read_b128 v[182:185], v153 offset:16384
	ds_read_b128 v[186:189], v153 offset:17408
	ds_read_b128 v[194:197], v153 offset:18432
	ds_read_b128 v[198:201], v153 offset:19456
	ds_read_b128 v[202:205], v153 offset:20480
	ds_read_b128 v[206:209], v153 offset:21504
	ds_read_b128 v[210:213], v153 offset:22528
	ds_read_b128 v[214:217], v153 offset:23552
	global_load_lds_dwordx4 v130, s[36:37]
	s_add_i32 m0, s65, 0x2000
	s_add_u32 s66, s36, 0x40000
	s_addc_u32 s67, s37, 0
	s_add_i32 s65, s51, s0
	global_load_lds_dwordx4 v134, s[36:37]
	s_mov_b32 m0, s65
	s_nop 0
	global_load_lds_dwordx4 v130, s[66:67]
	s_add_i32 m0, s65, 0x2000
	s_nop 0
	global_load_lds_dwordx4 v134, s[66:67]
	s_mov_b32 m0, s1
	s_nop 0
	global_load_lds_dwordx4 v128, s[40:41]
	s_mov_b32 m0, s31
	s_nop 0
	global_load_lds_dwordx4 v132, s[40:41]
	s_waitcnt vmcnt(8)
	s_waitcnt lgkmcnt(0)
	s_barrier
	s_setprio 1
	s_waitcnt lgkmcnt(0)
	v_mfma_f32_16x16x32_bf16 v[60:63], v[144:147], v[182:185], v[60:63]
	v_mfma_f32_16x16x32_bf16 v[56:59], v[158:161], v[182:185], v[56:59]
	v_mfma_f32_16x16x32_bf16 v[44:47], v[144:147], v[194:197], v[44:47]
	v_mfma_f32_16x16x32_bf16 v[40:43], v[158:161], v[194:197], v[40:43]
	v_mfma_f32_16x16x32_bf16 v[28:31], v[144:147], v[202:205], v[28:31]
	v_mfma_f32_16x16x32_bf16 v[24:27], v[158:161], v[202:205], v[24:27]
	v_mfma_f32_16x16x32_bf16 v[12:15], v[144:147], v[210:213], v[12:15]
	v_mfma_f32_16x16x32_bf16 v[8:11], v[158:161], v[210:213], v[8:11]
	v_mfma_f32_16x16x32_bf16 v[60:63], v[154:157], v[186:189], v[60:63]
	v_mfma_f32_16x16x32_bf16 v[56:59], v[162:165], v[186:189], v[56:59]
	v_mfma_f32_16x16x32_bf16 v[44:47], v[154:157], v[198:201], v[44:47]
	v_mfma_f32_16x16x32_bf16 v[40:43], v[162:165], v[198:201], v[40:43]
	v_mfma_f32_16x16x32_bf16 v[28:31], v[154:157], v[206:209], v[28:31]
	v_mfma_f32_16x16x32_bf16 v[24:27], v[162:165], v[206:209], v[24:27]
	v_mfma_f32_16x16x32_bf16 v[12:15], v[154:157], v[214:217], v[12:15]
	v_mfma_f32_16x16x32_bf16 v[8:11], v[162:165], v[214:217], v[8:11]
	s_setprio 0
	s_setprio 1
	v_mfma_f32_16x16x32_bf16 v[52:55], v[166:169], v[182:185], v[52:55]
	v_mfma_f32_16x16x32_bf16 v[48:51], v[174:177], v[182:185], v[48:51]
	v_mfma_f32_16x16x32_bf16 v[36:39], v[166:169], v[194:197], v[36:39]
	v_mfma_f32_16x16x32_bf16 v[32:35], v[174:177], v[194:197], v[32:35]
	v_mfma_f32_16x16x32_bf16 v[20:23], v[166:169], v[202:205], v[20:23]
	v_mfma_f32_16x16x32_bf16 v[16:19], v[174:177], v[202:205], v[16:19]
	v_mfma_f32_16x16x32_bf16 v[4:7], v[166:169], v[210:213], v[4:7]
	v_mfma_f32_16x16x32_bf16 v[0:3], v[174:177], v[210:213], v[0:3]
	v_mfma_f32_16x16x32_bf16 v[52:55], v[170:173], v[186:189], v[52:55]
	v_mfma_f32_16x16x32_bf16 v[48:51], v[178:181], v[186:189], v[48:51]
	v_mfma_f32_16x16x32_bf16 v[36:39], v[170:173], v[198:201], v[36:39]
	v_mfma_f32_16x16x32_bf16 v[32:35], v[178:181], v[198:201], v[32:35]
	v_mfma_f32_16x16x32_bf16 v[20:23], v[170:173], v[206:209], v[20:23]
	v_mfma_f32_16x16x32_bf16 v[16:19], v[178:181], v[206:209], v[16:19]
	v_mfma_f32_16x16x32_bf16 v[4:7], v[170:173], v[214:217], v[4:7]
	v_mfma_f32_16x16x32_bf16 v[0:3], v[178:181], v[214:217], v[0:3]
	s_setprio 0
	s_barrier
; #define PG8_STAGE(bufoff, gbase, voff) do { _Pragma("unroll") for (int _i = 0; _i < 2; ++_i) \
;         __builtin_amdgcn_global_load_lds((const unsigned*)((const char*)(gbase) + (voff)[_i]), (PG8_LAS unsigned*)(lds + (bufoff) + ldsw + _i * 8192), 16, 0, 0); } while (0)
; #define PG8_LDA(dst, b, h) do { _Pragma("unroll") for (int m = 0; m < 4; ++m) _Pragma("unroll") for (int k = 0; k < 2; ++k) dst[m][k] = *(const PG8_LAS bf16x8*)(lds + PG8_SA(b, h) + aoff + m * 2048 + k * 1024); } while (0)
; #define PG8_LDB(dst, b, h) do { _Pragma("unroll") for (int n = 0; n < 2; ++n) _Pragma("unroll") for (int k = 0; k < 2; ++k) dst[n][k] = *(const PG8_LAS bf16x8*)(lds + PG8_SB(b, h) + boff + n * 2048 + k * 1024); } while (0)
; #define PG8_MMA(ai, bj, At, Bt) do { __builtin_amdgcn_s_setprio(1); _Pragma("unroll") for (int m = 0; m < 4; ++m) _Pragma("unroll") for (int n = 0; n < 2; ++n) _Pragma("unroll") for (int k = 0; k < 2; ++k) \
;         acc[ai][bj][m][n] = __builtin_amdgcn_mfma_f32_16x16x32_bf16(Bt[n][k], At[m][k], acc[ai][bj][m][n], 0, 0, 0); __builtin_amdgcn_s_setprio(0); } while (0)
; #define PG8_WAIT_V(n) asm volatile("s_waitcnt vmcnt(" #n ")" ::: "memory")
; #define PG8_WAIT_L(n) asm volatile("s_waitcnt lgkmcnt(" #n ")" ::: "memory")
; #define PG8_BAR __builtin_amdgcn_s_barrier()
; #define PG8_SCHED __builtin_amdgcn_sched_barrier(0)
; template <class Epi, class Sched, bool ALIGN_EPI = false, bool SP2 = false>
; __device__ __forceinline__ void gemm_phase(PG8_LAS unsigned char* lds, const Gemm g, const Sched& S, const Epi& E) {
;     ...
;             PG8_LDB(B0, 1, 0); PG8_LDB(B1, 1, 1); PG8_SCHED; PG8_LDA(At, 1, 0); PG8_STAGE(PG8_SA(0, 1), a2 + hstep, voffA);
;             PG8_WAIT_V(8); PG8_WAIT_L(0); PG8_BAR; PG8_MMA(0, 0, At, B0); PG8_MMA(0, 1, At, B1); PG8_BAR; PG8_SCHED;
;             PG8_LDA(At, 1, 1); PG8_STAGE(PG8_SB(1, 0), b3, voffB); PG8_STAGE(PG8_SB(1, 1), b3 + hstep, voffB); PG8_STAGE(PG8_SA(1, 0), a3, voffA);
;             PG8_WAIT_V(8); PG8_WAIT_L(0); PG8_BAR; PG8_MMA(1, 0, At, B0); PG8_MMA(1, 1, At, B1); PG8_BAR; PG8_SCHED;
	s_add_i32 s65, 0, 0x18000
	s_add_i32 s66, 0, 0x1c000
	v_add_u32_e32 v162, s65, v149
	v_add_u32_e32 v178, s66, v149
	ds_read_b128 v[144:147], v162
	ds_read_b128 v[154:157], v162 offset:1024
	ds_read_b128 v[158:161], v162 offset:2048
	ds_read_b128 v[162:165], v162 offset:3072
	ds_read_b128 v[166:169], v178
	ds_read_b128 v[170:173], v178 offset:1024
	ds_read_b128 v[174:177], v178 offset:2048
	ds_read_b128 v[178:181], v178 offset:3072
	s_add_u32 s40, s40, 0x40000
	s_addc_u32 s41, s41, 0
	s_mov_b32 m0, s38
	ds_read_b128 v[182:185], v153 offset:32768
	ds_read_b128 v[186:189], v153 offset:33792
	ds_read_b128 v[194:197], v153 offset:34816
	ds_read_b128 v[198:201], v153 offset:35840
	ds_read_b128 v[202:205], v153 offset:36864
	ds_read_b128 v[206:209], v153 offset:37888
	ds_read_b128 v[210:213], v153 offset:38912
	ds_read_b128 v[214:217], v153 offset:39936
	global_load_lds_dwordx4 v128, s[40:41]
	s_mov_b32 m0, s39
	s_nop 0
	global_load_lds_dwordx4 v132, s[40:41]
	s_waitcnt vmcnt(8)
	s_waitcnt lgkmcnt(0)
	s_barrier
	s_setprio 1
	s_waitcnt lgkmcnt(0)
	v_mfma_f32_16x16x32_bf16 v[124:127], v[144:147], v[182:185], v[124:127]
	v_mfma_f32_16x16x32_bf16 v[120:123], v[158:161], v[182:185], v[120:123]
	v_mfma_f32_16x16x32_bf16 v[108:111], v[144:147], v[194:197], v[108:111]
	v_mfma_f32_16x16x32_bf16 v[104:107], v[158:161], v[194:197], v[104:107]
	v_mfma_f32_16x16x32_bf16 v[92:95], v[144:147], v[202:205], v[92:95]
	v_mfma_f32_16x16x32_bf16 v[88:91], v[158:161], v[202:205], v[88:91]
	v_mfma_f32_16x16x32_bf16 v[76:79], v[144:147], v[210:213], v[76:79]
	v_mfma_f32_16x16x32_bf16 v[72:75], v[158:161], v[210:213], v[72:75]
	v_mfma_f32_16x16x32_bf16 v[124:127], v[154:157], v[186:189], v[124:127]
	v_mfma_f32_16x16x32_bf16 v[120:123], v[162:165], v[186:189], v[120:123]
	v_mfma_f32_16x16x32_bf16 v[108:111], v[154:157], v[198:201], v[108:111]
	v_mfma_f32_16x16x32_bf16 v[104:107], v[162:165], v[198:201], v[104:107]
	v_mfma_f32_16x16x32_bf16 v[92:95], v[154:157], v[206:209], v[92:95]
	v_mfma_f32_16x16x32_bf16 v[88:91], v[162:165], v[206:209], v[88:91]
	v_mfma_f32_16x16x32_bf16 v[76:79], v[154:157], v[214:217], v[76:79]
	v_mfma_f32_16x16x32_bf16 v[72:75], v[162:165], v[214:217], v[72:75]
	s_setprio 0
	s_setprio 1
	v_mfma_f32_16x16x32_bf16 v[116:119], v[166:169], v[182:185], v[116:119]
	v_mfma_f32_16x16x32_bf16 v[112:115], v[174:177], v[182:185], v[112:115]
	v_mfma_f32_16x16x32_bf16 v[100:103], v[166:169], v[194:197], v[100:103]
	v_mfma_f32_16x16x32_bf16 v[96:99], v[174:177], v[194:197], v[96:99]
	v_mfma_f32_16x16x32_bf16 v[84:87], v[166:169], v[202:205], v[84:87]
	v_mfma_f32_16x16x32_bf16 v[80:83], v[174:177], v[202:205], v[80:83]
	v_mfma_f32_16x16x32_bf16 v[68:71], v[166:169], v[210:213], v[68:71]
	v_mfma_f32_16x16x32_bf16 v[64:67], v[174:177], v[210:213], v[64:67]
	v_mfma_f32_16x16x32_bf16 v[116:119], v[170:173], v[186:189], v[116:119]
	v_mfma_f32_16x16x32_bf16 v[112:115], v[178:181], v[186:189], v[112:115]
	v_mfma_f32_16x16x32_bf16 v[100:103], v[170:173], v[198:201], v[100:103]
	v_mfma_f32_16x16x32_bf16 v[96:99], v[178:181], v[198:201], v[96:99]
	v_mfma_f32_16x16x32_bf16 v[84:87], v[170:173], v[206:209], v[84:87]
	v_mfma_f32_16x16x32_bf16 v[80:83], v[178:181], v[206:209], v[80:83]
	v_mfma_f32_16x16x32_bf16 v[68:71], v[170:173], v[214:217], v[68:71]
	v_mfma_f32_16x16x32_bf16 v[64:67], v[178:181], v[214:217], v[64:67]
	s_setprio 0
	s_barrier
	s_add_i32 s40, s65, s0
	s_mov_b32 m0, s40
	ds_read_b128 v[182:185], v153 offset:49152
	ds_read_b128 v[186:189], v153 offset:50176
	ds_read_b128 v[194:197], v153 offset:51200
	ds_read_b128 v[198:201], v153 offset:52224
	ds_read_b128 v[202:205], v153 offset:53248
	ds_read_b128 v[206:209], v153 offset:54272
	ds_read_b128 v[210:213], v153 offset:55296
	ds_read_b128 v[214:217], v153 offset:56320
	global_load_lds_dwordx4 v130, vcc
	s_add_i32 m0, s40, 0x2000
	s_add_u32 s36, s36, 0x40080
	s_addc_u32 s37, s37, 0
	s_add_i32 s40, s66, s0
	global_load_lds_dwordx4 v134, vcc
	s_mov_b32 m0, s40
	s_nop 0
	global_load_lds_dwordx4 v130, s[36:37]
	s_add_i32 m0, s40, 0x2000
	s_nop 0
	global_load_lds_dwordx4 v134, s[36:37]
	s_mov_b32 m0, s44
	s_nop 0
	global_load_lds_dwordx4 v128, s[100:101]
	s_mov_b32 m0, s45
	s_nop 0
	global_load_lds_dwordx4 v132, s[100:101]
	s_waitcnt vmcnt(8)
	s_waitcnt lgkmcnt(0)
	s_barrier
	s_setprio 1
	s_waitcnt lgkmcnt(0)
	v_mfma_f32_16x16x32_bf16 v[60:63], v[144:147], v[182:185], v[60:63]
	v_mfma_f32_16x16x32_bf16 v[56:59], v[158:161], v[182:185], v[56:59]
	v_mfma_f32_16x16x32_bf16 v[44:47], v[144:147], v[194:197], v[44:47]
	v_mfma_f32_16x16x32_bf16 v[40:43], v[158:161], v[194:197], v[40:43]
	v_mfma_f32_16x16x32_bf16 v[28:31], v[144:147], v[202:205], v[28:31]
	v_mfma_f32_16x16x32_bf16 v[24:27], v[158:161], v[202:205], v[24:27]
	v_mfma_f32_16x16x32_bf16 v[12:15], v[144:147], v[210:213], v[12:15]
	v_mfma_f32_16x16x32_bf16 v[8:11], v[158:161], v[210:213], v[8:11]
	v_mfma_f32_16x16x32_bf16 v[60:63], v[154:157], v[186:189], v[60:63]
	v_mfma_f32_16x16x32_bf16 v[56:59], v[162:165], v[186:189], v[56:59]
	v_mfma_f32_16x16x32_bf16 v[44:47], v[154:157], v[198:201], v[44:47]
	v_mfma_f32_16x16x32_bf16 v[40:43], v[162:165], v[198:201], v[40:43]
	v_mfma_f32_16x16x32_bf16 v[28:31], v[154:157], v[206:209], v[28:31]
	v_mfma_f32_16x16x32_bf16 v[24:27], v[162:165], v[206:209], v[24:27]
	v_mfma_f32_16x16x32_bf16 v[12:15], v[154:157], v[214:217], v[12:15]
	v_mfma_f32_16x16x32_bf16 v[8:11], v[162:165], v[214:217], v[8:11]
	s_setprio 0
	s_setprio 1
	v_mfma_f32_16x16x32_bf16 v[52:55], v[166:169], v[182:185], v[52:55]
	v_mfma_f32_16x16x32_bf16 v[48:51], v[174:177], v[182:185], v[48:51]
	v_mfma_f32_16x16x32_bf16 v[36:39], v[166:169], v[194:197], v[36:39]
	v_mfma_f32_16x16x32_bf16 v[32:35], v[174:177], v[194:197], v[32:35]
	v_mfma_f32_16x16x32_bf16 v[20:23], v[166:169], v[202:205], v[20:23]
	v_mfma_f32_16x16x32_bf16 v[16:19], v[174:177], v[202:205], v[16:19]
	v_mfma_f32_16x16x32_bf16 v[4:7], v[166:169], v[210:213], v[4:7]
	v_mfma_f32_16x16x32_bf16 v[0:3], v[174:177], v[210:213], v[0:3]
	v_mfma_f32_16x16x32_bf16 v[52:55], v[170:173], v[186:189], v[52:55]
	v_mfma_f32_16x16x32_bf16 v[48:51], v[178:181], v[186:189], v[48:51]
	v_mfma_f32_16x16x32_bf16 v[36:39], v[170:173], v[198:201], v[36:39]
	v_mfma_f32_16x16x32_bf16 v[32:35], v[178:181], v[198:201], v[32:35]
	v_mfma_f32_16x16x32_bf16 v[20:23], v[170:173], v[206:209], v[20:23]
	v_mfma_f32_16x16x32_bf16 v[16:19], v[178:181], v[206:209], v[16:19]
	v_mfma_f32_16x16x32_bf16 v[4:7], v[170:173], v[214:217], v[4:7]
	v_mfma_f32_16x16x32_bf16 v[0:3], v[178:181], v[214:217], v[0:3]
	s_setprio 0
	s_barrier
	s_add_i32 s64, s64, 2
	s_add_u32 s34, s34, 0x100
	s_addc_u32 s35, s35, 0
	s_add_u32 s62, s62, 0x100
	s_addc_u32 s63, s63, 0
	s_cmp_gt_u32 s64, 13
	s_cbranch_scc0 .LBB0_413
	s_and_b64 vcc, exec, s[18:19]
	s_cbranch_vccz .LBB0_416
	s_barrier

; #define PG8_STAGE(bufoff, gbase, voff) do { _Pragma("unroll") for (int _i = 0; _i < 2; ++_i) \
;         __builtin_amdgcn_global_load_lds((const unsigned*)((const char*)(gbase) + (voff)[_i]), (PG8_LAS unsigned*)(lds + (bufoff) + ldsw + _i * 8192), 16, 0, 0); } while (0)
; #define PG8_LDA(dst, b, h) do { _Pragma("unroll") for (int m = 0; m < 4; ++m) _Pragma("unroll") for (int k = 0; k < 2; ++k) dst[m][k] = *(const PG8_LAS bf16x8*)(lds + PG8_SA(b, h) + aoff + m * 2048 + k * 1024); } while (0)
; #define PG8_LDB(dst, b, h) do { _Pragma("unroll") for (int n = 0; n < 2; ++n) _Pragma("unroll") for (int k = 0; k < 2; ++k) dst[n][k] = *(const PG8_LAS bf16x8*)(lds + PG8_SB(b, h) + boff + n * 2048 + k * 1024); } while (0)
; #define PG8_MMA(ai, bj, At, Bt) do { __builtin_amdgcn_s_setprio(1); _Pragma("unroll") for (int m = 0; m < 4; ++m) _Pragma("unroll") for (int n = 0; n < 2; ++n) _Pragma("unroll") for (int k = 0; k < 2; ++k) \
;         acc[ai][bj][m][n] = __builtin_amdgcn_mfma_f32_16x16x32_bf16(Bt[n][k], At[m][k], acc[ai][bj][m][n], 0, 0, 0); __builtin_amdgcn_s_setprio(0); } while (0)
; #define PG8_WAIT_V(n) asm volatile("s_waitcnt vmcnt(" #n ")" ::: "memory")
; #define PG8_WAIT_L(n) asm volatile("s_waitcnt lgkmcnt(" #n ")" ::: "memory")
; #define PG8_BAR __builtin_amdgcn_s_barrier()
; #define PG8_SCHED __builtin_amdgcn_sched_barrier(0)
; template <class Epi, class Sched, bool ALIGN_EPI = false, bool SP2 = false>
; __device__ __forceinline__ void gemm_phase(PG8_LAS unsigned char* lds, const Gemm g, const Sched& S, const Epi& E) {
;     ...
;             PG8_LDB(B0, 0, 0); PG8_LDB(B1, 0, 1); PG8_SCHED; PG8_LDA(At, 0, 0); PG8_STAGE(PG8_SA(1, 1), a1 + hstep, voffA);
;             PG8_WAIT_V(8); PG8_WAIT_L(0); PG8_BAR; PG8_MMA(0, 0, At, B0); PG8_MMA(0, 1, At, B1); PG8_BAR; PG8_SCHED;
;             PG8_LDA(At, 0, 1); PG8_STAGE(PG8_SB(0, 0), b2, voffB); PG8_STAGE(PG8_SB(0, 1), b2 + hstep, voffB); PG8_STAGE(PG8_SA(0, 0), a2, voffA);
;             PG8_WAIT_V(8); PG8_WAIT_L(0); PG8_BAR; PG8_MMA(1, 0, At, B0); PG8_MMA(1, 1, At, B1); PG8_BAR; PG8_SCHED;
.LBB0_462:
	ds_read_b128 v[156:159], v151
	ds_read_b128 v[160:163], v151 offset:1024
	ds_read_b128 v[164:167], v151 offset:2048
	ds_read_b128 v[168:171], v151 offset:3072
	ds_read_b128 v[172:175], v152
	ds_read_b128 v[176:179], v152 offset:1024
	ds_read_b128 v[180:183], v152 offset:2048
	ds_read_b128 v[184:187], v152 offset:3072
	s_add_u32 s26, s24, 0xfffc0080
	s_addc_u32 s27, s25, -1
	s_cmp_eq_u32 s50, 12
	s_cselect_b32 s29, s17, s27
	s_cselect_b32 s28, s41, s26
	s_cselect_b32 s27, s11, s45
	s_cselect_b32 s26, s42, s44
	s_add_u32 vcc_lo, s26, 0x80
	s_addc_u32 vcc_hi, s27, 0
	s_add_u32 s100, s28, 0x80
	s_addc_u32 s101, s29, 0
	s_add_i32 m0, s1, 0xc000
	ds_read_b128 v[194:197], v153
	ds_read_b128 v[198:201], v153 offset:1024
	ds_read_b128 v[202:205], v153 offset:2048
	ds_read_b128 v[206:209], v153 offset:3072
	ds_read_b128 v[210:213], v153 offset:4096
	ds_read_b128 v[214:217], v153 offset:5120
	ds_read_b128 v[218:221], v153 offset:6144
	ds_read_b128 v[222:225], v153 offset:7168
	global_load_lds_dwordx4 v138, s[24:25]
	s_add_i32 m0, s1, 0xe000
	s_nop 0
	global_load_lds_dwordx4 v140, s[24:25]
	s_waitcnt vmcnt(8)
	s_waitcnt lgkmcnt(0)
	s_barrier
	s_setprio 1
	s_waitcnt lgkmcnt(0)
	v_mfma_f32_16x16x32_bf16 v[124:127], v[156:159], v[194:197], v[124:127]
	v_mfma_f32_16x16x32_bf16 v[120:123], v[164:167], v[194:197], v[120:123]
	v_mfma_f32_16x16x32_bf16 v[108:111], v[156:159], v[202:205], v[108:111]
	v_mfma_f32_16x16x32_bf16 v[104:107], v[164:167], v[202:205], v[104:107]
	v_mfma_f32_16x16x32_bf16 v[92:95], v[156:159], v[210:213], v[92:95]
	v_mfma_f32_16x16x32_bf16 v[88:91], v[164:167], v[210:213], v[88:91]
	v_mfma_f32_16x16x32_bf16 v[76:79], v[156:159], v[218:221], v[76:79]
	v_mfma_f32_16x16x32_bf16 v[72:75], v[164:167], v[218:221], v[72:75]
	v_mfma_f32_16x16x32_bf16 v[124:127], v[160:163], v[198:201], v[124:127]
	v_mfma_f32_16x16x32_bf16 v[120:123], v[168:171], v[198:201], v[120:123]
	v_mfma_f32_16x16x32_bf16 v[108:111], v[160:163], v[206:209], v[108:111]
	v_mfma_f32_16x16x32_bf16 v[104:107], v[168:171], v[206:209], v[104:107]
	v_mfma_f32_16x16x32_bf16 v[92:95], v[160:163], v[214:217], v[92:95]
	v_mfma_f32_16x16x32_bf16 v[88:91], v[168:171], v[214:217], v[88:91]
	v_mfma_f32_16x16x32_bf16 v[76:79], v[160:163], v[222:225], v[76:79]
	v_mfma_f32_16x16x32_bf16 v[72:75], v[168:171], v[222:225], v[72:75]
	s_setprio 0
	s_setprio 1
	v_mfma_f32_16x16x32_bf16 v[116:119], v[172:175], v[194:197], v[116:119]
	v_mfma_f32_16x16x32_bf16 v[112:115], v[180:183], v[194:197], v[112:115]
	v_mfma_f32_16x16x32_bf16 v[100:103], v[172:175], v[202:205], v[100:103]
	v_mfma_f32_16x16x32_bf16 v[96:99], v[180:183], v[202:205], v[96:99]
	v_mfma_f32_16x16x32_bf16 v[84:87], v[172:175], v[210:213], v[84:87]
	v_mfma_f32_16x16x32_bf16 v[80:83], v[180:183], v[210:213], v[80:83]
	v_mfma_f32_16x16x32_bf16 v[68:71], v[172:175], v[218:221], v[68:71]
	v_mfma_f32_16x16x32_bf16 v[64:67], v[180:183], v[218:221], v[64:67]
	v_mfma_f32_16x16x32_bf16 v[116:119], v[176:179], v[198:201], v[116:119]
	v_mfma_f32_16x16x32_bf16 v[112:115], v[184:187], v[198:201], v[112:115]
	v_mfma_f32_16x16x32_bf16 v[100:103], v[176:179], v[206:209], v[100:103]
	v_mfma_f32_16x16x32_bf16 v[96:99], v[184:187], v[206:209], v[96:99]
	v_mfma_f32_16x16x32_bf16 v[84:87], v[176:179], v[214:217], v[84:87]
	v_mfma_f32_16x16x32_bf16 v[80:83], v[184:187], v[214:217], v[80:83]
	v_mfma_f32_16x16x32_bf16 v[68:71], v[176:179], v[222:225], v[68:71]
	v_mfma_f32_16x16x32_bf16 v[64:67], v[184:187], v[222:225], v[64:67]
	s_setprio 0
	s_barrier
	s_add_i32 s51, s38, s0
	s_mov_b32 m0, s51
	ds_read_b128 v[194:197], v153 offset:16384
	ds_read_b128 v[198:201], v153 offset:17408
	ds_read_b128 v[202:205], v153 offset:18432
	ds_read_b128 v[206:209], v153 offset:19456
	ds_read_b128 v[210:213], v153 offset:20480
	ds_read_b128 v[214:217], v153 offset:21504
	ds_read_b128 v[218:221], v153 offset:22528
	ds_read_b128 v[222:225], v153 offset:23552
	global_load_lds_dwordx4 v132, s[26:27]
	s_add_i32 m0, s51, 0x2000
	s_add_u32 s56, s26, 0x40000
	s_addc_u32 s57, s27, 0
	s_add_i32 s51, s39, s0
	global_load_lds_dwordx4 v128, s[26:27]
	s_mov_b32 m0, s51
	s_nop 0
	global_load_lds_dwordx4 v132, s[56:57]
	s_add_i32 m0, s51, 0x2000
	s_nop 0
	global_load_lds_dwordx4 v128, s[56:57]
	s_mov_b32 m0, s1
	s_nop 0
	global_load_lds_dwordx4 v134, s[28:29]
	s_mov_b32 m0, s23
	s_nop 0
	global_load_lds_dwordx4 v130, s[28:29]
	s_waitcnt vmcnt(8)
	s_waitcnt lgkmcnt(0)
	s_barrier
	s_setprio 1
	s_waitcnt lgkmcnt(0)
	v_mfma_f32_16x16x32_bf16 v[60:63], v[156:159], v[194:197], v[60:63]
	v_mfma_f32_16x16x32_bf16 v[56:59], v[164:167], v[194:197], v[56:59]
	v_mfma_f32_16x16x32_bf16 v[44:47], v[156:159], v[202:205], v[44:47]
	v_mfma_f32_16x16x32_bf16 v[40:43], v[164:167], v[202:205], v[40:43]
	v_mfma_f32_16x16x32_bf16 v[28:31], v[156:159], v[210:213], v[28:31]
	v_mfma_f32_16x16x32_bf16 v[24:27], v[164:167], v[210:213], v[24:27]
	v_mfma_f32_16x16x32_bf16 v[12:15], v[156:159], v[218:221], v[12:15]
	v_mfma_f32_16x16x32_bf16 v[8:11], v[164:167], v[218:221], v[8:11]
	v_mfma_f32_16x16x32_bf16 v[60:63], v[160:163], v[198:201], v[60:63]
	v_mfma_f32_16x16x32_bf16 v[56:59], v[168:171], v[198:201], v[56:59]
	v_mfma_f32_16x16x32_bf16 v[44:47], v[160:163], v[206:209], v[44:47]
	v_mfma_f32_16x16x32_bf16 v[40:43], v[168:171], v[206:209], v[40:43]
	v_mfma_f32_16x16x32_bf16 v[28:31], v[160:163], v[214:217], v[28:31]
	v_mfma_f32_16x16x32_bf16 v[24:27], v[168:171], v[214:217], v[24:27]
	v_mfma_f32_16x16x32_bf16 v[12:15], v[160:163], v[222:225], v[12:15]
	v_mfma_f32_16x16x32_bf16 v[8:11], v[168:171], v[222:225], v[8:11]
	s_setprio 0
	s_setprio 1
	v_mfma_f32_16x16x32_bf16 v[52:55], v[172:175], v[194:197], v[52:55]
	v_mfma_f32_16x16x32_bf16 v[48:51], v[180:183], v[194:197], v[48:51]
	v_mfma_f32_16x16x32_bf16 v[36:39], v[172:175], v[202:205], v[36:39]
	v_mfma_f32_16x16x32_bf16 v[32:35], v[180:183], v[202:205], v[32:35]
	v_mfma_f32_16x16x32_bf16 v[20:23], v[172:175], v[210:213], v[20:23]
	v_mfma_f32_16x16x32_bf16 v[16:19], v[180:183], v[210:213], v[16:19]
	v_mfma_f32_16x16x32_bf16 v[4:7], v[172:175], v[218:221], v[4:7]
	v_mfma_f32_16x16x32_bf16 v[0:3], v[180:183], v[218:221], v[0:3]
	v_mfma_f32_16x16x32_bf16 v[52:55], v[176:179], v[198:201], v[52:55]
	v_mfma_f32_16x16x32_bf16 v[48:51], v[184:187], v[198:201], v[48:51]
	v_mfma_f32_16x16x32_bf16 v[36:39], v[176:179], v[206:209], v[36:39]
	v_mfma_f32_16x16x32_bf16 v[32:35], v[184:187], v[206:209], v[32:35]
	v_mfma_f32_16x16x32_bf16 v[20:23], v[176:179], v[214:217], v[20:23]
	v_mfma_f32_16x16x32_bf16 v[16:19], v[184:187], v[214:217], v[16:19]
	v_mfma_f32_16x16x32_bf16 v[4:7], v[176:179], v[222:225], v[4:7]
	v_mfma_f32_16x16x32_bf16 v[0:3], v[184:187], v[222:225], v[0:3]
	s_setprio 0
	s_barrier
; #define PG8_STAGE(bufoff, gbase, voff) do { _Pragma("unroll") for (int _i = 0; _i < 2; ++_i) \
;         __builtin_amdgcn_global_load_lds((const unsigned*)((const char*)(gbase) + (voff)[_i]), (PG8_LAS unsigned*)(lds + (bufoff) + ldsw + _i * 8192), 16, 0, 0); } while (0)
; #define PG8_LDA(dst, b, h) do { _Pragma("unroll") for (int m = 0; m < 4; ++m) _Pragma("unroll") for (int k = 0; k < 2; ++k) dst[m][k] = *(const PG8_LAS bf16x8*)(lds + PG8_SA(b, h) + aoff + m * 2048 + k * 1024); } while (0)
; #define PG8_LDB(dst, b, h) do { _Pragma("unroll") for (int n = 0; n < 2; ++n) _Pragma("unroll") for (int k = 0; k < 2; ++k) dst[n][k] = *(const PG8_LAS bf16x8*)(lds + PG8_SB(b, h) + boff + n * 2048 + k * 1024); } while (0)
; #define PG8_MMA(ai, bj, At, Bt) do { __builtin_amdgcn_s_setprio(1); _Pragma("unroll") for (int m = 0; m < 4; ++m) _Pragma("unroll") for (int n = 0; n < 2; ++n) _Pragma("unroll") for (int k = 0; k < 2; ++k) \
;         acc[ai][bj][m][n] = __builtin_amdgcn_mfma_f32_16x16x32_bf16(Bt[n][k], At[m][k], acc[ai][bj][m][n], 0, 0, 0); __builtin_amdgcn_s_setprio(0); } while (0)
; #define PG8_WAIT_V(n) asm volatile("s_waitcnt vmcnt(" #n ")" ::: "memory")
; #define PG8_WAIT_L(n) asm volatile("s_waitcnt lgkmcnt(" #n ")" ::: "memory")
; #define PG8_BAR __builtin_amdgcn_s_barrier()
; #define PG8_SCHED __builtin_amdgcn_sched_barrier(0)
; template <class Epi, class Sched, bool ALIGN_EPI = false, bool SP2 = false>
; __device__ __forceinline__ void gemm_phase(PG8_LAS unsigned char* lds, const Gemm g, const Sched& S, const Epi& E) {
;     ...
;             PG8_LDB(B0, 1, 0); PG8_LDB(B1, 1, 1); PG8_SCHED; PG8_LDA(At, 1, 0); PG8_STAGE(PG8_SA(0, 1), a2 + hstep, voffA);
;             PG8_WAIT_V(8); PG8_WAIT_L(0); PG8_BAR; PG8_MMA(0, 0, At, B0); PG8_MMA(0, 1, At, B1); PG8_BAR; PG8_SCHED;
;             PG8_LDA(At, 1, 1); PG8_STAGE(PG8_SB(1, 0), b3, voffB); PG8_STAGE(PG8_SB(1, 1), b3 + hstep, voffB); PG8_STAGE(PG8_SA(1, 0), a3, voffA);
;             PG8_WAIT_V(8); PG8_WAIT_L(0); PG8_BAR; PG8_MMA(1, 0, At, B0); PG8_MMA(1, 1, At, B1); PG8_BAR; PG8_SCHED;
	s_add_i32 s51, 0, 0x18000
	v_add_u32_e32 v155, s51, v149
	s_add_i32 s56, 0, 0x1c000
	ds_read_b128 v[156:159], v155
	ds_read_b128 v[160:163], v155 offset:1024
	ds_read_b128 v[164:167], v155 offset:2048
	ds_read_b128 v[168:171], v155 offset:3072
	v_add_u32_e32 v155, s56, v149
	ds_read_b128 v[172:175], v155
	ds_read_b128 v[176:179], v155 offset:1024
	ds_read_b128 v[180:183], v155 offset:2048
	ds_read_b128 v[184:187], v155 offset:3072
	s_add_u32 s28, s28, 0x40000
	s_addc_u32 s29, s29, 0
	s_mov_b32 m0, s31
	ds_read_b128 v[194:197], v153 offset:32768
	ds_read_b128 v[198:201], v153 offset:33792
	ds_read_b128 v[202:205], v153 offset:34816
	ds_read_b128 v[206:209], v153 offset:35840
	ds_read_b128 v[210:213], v153 offset:36864
	ds_read_b128 v[214:217], v153 offset:37888
	ds_read_b128 v[218:221], v153 offset:38912
	ds_read_b128 v[222:225], v153 offset:39936
	global_load_lds_dwordx4 v134, s[28:29]
	s_mov_b32 m0, s34
	s_nop 0
	global_load_lds_dwordx4 v130, s[28:29]
	s_waitcnt vmcnt(8)
	s_waitcnt lgkmcnt(0)
	s_barrier
	s_setprio 1
	s_waitcnt lgkmcnt(0)
	v_mfma_f32_16x16x32_bf16 v[124:127], v[156:159], v[194:197], v[124:127]
	v_mfma_f32_16x16x32_bf16 v[120:123], v[164:167], v[194:197], v[120:123]
	v_mfma_f32_16x16x32_bf16 v[108:111], v[156:159], v[202:205], v[108:111]
	v_mfma_f32_16x16x32_bf16 v[104:107], v[164:167], v[202:205], v[104:107]
	v_mfma_f32_16x16x32_bf16 v[92:95], v[156:159], v[210:213], v[92:95]
	v_mfma_f32_16x16x32_bf16 v[88:91], v[164:167], v[210:213], v[88:91]
	v_mfma_f32_16x16x32_bf16 v[76:79], v[156:159], v[218:221], v[76:79]
	v_mfma_f32_16x16x32_bf16 v[72:75], v[164:167], v[218:221], v[72:75]
	v_mfma_f32_16x16x32_bf16 v[124:127], v[160:163], v[198:201], v[124:127]
	v_mfma_f32_16x16x32_bf16 v[120:123], v[168:171], v[198:201], v[120:123]
	v_mfma_f32_16x16x32_bf16 v[108:111], v[160:163], v[206:209], v[108:111]
	v_mfma_f32_16x16x32_bf16 v[104:107], v[168:171], v[206:209], v[104:107]
	v_mfma_f32_16x16x32_bf16 v[92:95], v[160:163], v[214:217], v[92:95]
	v_mfma_f32_16x16x32_bf16 v[88:91], v[168:171], v[214:217], v[88:91]
	v_mfma_f32_16x16x32_bf16 v[76:79], v[160:163], v[222:225], v[76:79]
	v_mfma_f32_16x16x32_bf16 v[72:75], v[168:171], v[222:225], v[72:75]
	s_setprio 0
	s_setprio 1
	v_mfma_f32_16x16x32_bf16 v[116:119], v[172:175], v[194:197], v[116:119]
	v_mfma_f32_16x16x32_bf16 v[112:115], v[180:183], v[194:197], v[112:115]
	v_mfma_f32_16x16x32_bf16 v[100:103], v[172:175], v[202:205], v[100:103]
	v_mfma_f32_16x16x32_bf16 v[96:99], v[180:183], v[202:205], v[96:99]
	v_mfma_f32_16x16x32_bf16 v[84:87], v[172:175], v[210:213], v[84:87]
	v_mfma_f32_16x16x32_bf16 v[80:83], v[180:183], v[210:213], v[80:83]
	v_mfma_f32_16x16x32_bf16 v[68:71], v[172:175], v[218:221], v[68:71]
	v_mfma_f32_16x16x32_bf16 v[64:67], v[180:183], v[218:221], v[64:67]
	v_mfma_f32_16x16x32_bf16 v[116:119], v[176:179], v[198:201], v[116:119]
	v_mfma_f32_16x16x32_bf16 v[112:115], v[184:187], v[198:201], v[112:115]
	v_mfma_f32_16x16x32_bf16 v[100:103], v[176:179], v[206:209], v[100:103]
	v_mfma_f32_16x16x32_bf16 v[96:99], v[184:187], v[206:209], v[96:99]
	v_mfma_f32_16x16x32_bf16 v[84:87], v[176:179], v[214:217], v[84:87]
	v_mfma_f32_16x16x32_bf16 v[80:83], v[184:187], v[214:217], v[80:83]
	v_mfma_f32_16x16x32_bf16 v[68:71], v[176:179], v[222:225], v[68:71]
	v_mfma_f32_16x16x32_bf16 v[64:67], v[184:187], v[222:225], v[64:67]
	s_setprio 0
	s_barrier
	s_add_i32 s28, s51, s0
	s_mov_b32 m0, s28
	ds_read_b128 v[194:197], v153 offset:49152
	ds_read_b128 v[198:201], v153 offset:50176
	ds_read_b128 v[202:205], v153 offset:51200
	ds_read_b128 v[206:209], v153 offset:52224
	ds_read_b128 v[210:213], v153 offset:53248
	ds_read_b128 v[214:217], v153 offset:54272
	ds_read_b128 v[218:221], v153 offset:55296
	ds_read_b128 v[222:225], v153 offset:56320
	global_load_lds_dwordx4 v132, vcc
	s_add_i32 m0, s28, 0x2000
	s_add_u32 s26, s26, 0x40080
	s_addc_u32 s27, s27, 0
	s_add_i32 s28, s56, s0
	global_load_lds_dwordx4 v128, vcc
	s_mov_b32 m0, s28
	s_nop 0
	global_load_lds_dwordx4 v132, s[26:27]
	s_add_i32 m0, s28, 0x2000
	s_nop 0
	global_load_lds_dwordx4 v128, s[26:27]
	s_mov_b32 m0, s36
	s_nop 0
	global_load_lds_dwordx4 v134, s[100:101]
	s_mov_b32 m0, s37
	s_nop 0
	global_load_lds_dwordx4 v130, s[100:101]
	s_waitcnt vmcnt(8)
	s_waitcnt lgkmcnt(0)
	s_barrier
	s_setprio 1
	s_waitcnt lgkmcnt(0)
	v_mfma_f32_16x16x32_bf16 v[60:63], v[156:159], v[194:197], v[60:63]
	v_mfma_f32_16x16x32_bf16 v[56:59], v[164:167], v[194:197], v[56:59]
	v_mfma_f32_16x16x32_bf16 v[44:47], v[156:159], v[202:205], v[44:47]
	v_mfma_f32_16x16x32_bf16 v[40:43], v[164:167], v[202:205], v[40:43]
	v_mfma_f32_16x16x32_bf16 v[28:31], v[156:159], v[210:213], v[28:31]
	v_mfma_f32_16x16x32_bf16 v[24:27], v[164:167], v[210:213], v[24:27]
	v_mfma_f32_16x16x32_bf16 v[12:15], v[156:159], v[218:221], v[12:15]
	v_mfma_f32_16x16x32_bf16 v[8:11], v[164:167], v[218:221], v[8:11]
	v_mfma_f32_16x16x32_bf16 v[60:63], v[160:163], v[198:201], v[60:63]
	v_mfma_f32_16x16x32_bf16 v[56:59], v[168:171], v[198:201], v[56:59]
	v_mfma_f32_16x16x32_bf16 v[44:47], v[160:163], v[206:209], v[44:47]
	v_mfma_f32_16x16x32_bf16 v[40:43], v[168:171], v[206:209], v[40:43]
	v_mfma_f32_16x16x32_bf16 v[28:31], v[160:163], v[214:217], v[28:31]
	v_mfma_f32_16x16x32_bf16 v[24:27], v[168:171], v[214:217], v[24:27]
	v_mfma_f32_16x16x32_bf16 v[12:15], v[160:163], v[222:225], v[12:15]
	v_mfma_f32_16x16x32_bf16 v[8:11], v[168:171], v[222:225], v[8:11]
	s_setprio 0
	s_setprio 1
	v_mfma_f32_16x16x32_bf16 v[52:55], v[172:175], v[194:197], v[52:55]
	v_mfma_f32_16x16x32_bf16 v[48:51], v[180:183], v[194:197], v[48:51]
	v_mfma_f32_16x16x32_bf16 v[36:39], v[172:175], v[202:205], v[36:39]
	v_mfma_f32_16x16x32_bf16 v[32:35], v[180:183], v[202:205], v[32:35]
	v_mfma_f32_16x16x32_bf16 v[20:23], v[172:175], v[210:213], v[20:23]
	v_mfma_f32_16x16x32_bf16 v[16:19], v[180:183], v[210:213], v[16:19]
	v_mfma_f32_16x16x32_bf16 v[4:7], v[172:175], v[218:221], v[4:7]
	v_mfma_f32_16x16x32_bf16 v[0:3], v[180:183], v[218:221], v[0:3]
	v_mfma_f32_16x16x32_bf16 v[52:55], v[176:179], v[198:201], v[52:55]
	v_mfma_f32_16x16x32_bf16 v[48:51], v[184:187], v[198:201], v[48:51]
	v_mfma_f32_16x16x32_bf16 v[36:39], v[176:179], v[206:209], v[36:39]
	v_mfma_f32_16x16x32_bf16 v[32:35], v[184:187], v[206:209], v[32:35]
	v_mfma_f32_16x16x32_bf16 v[20:23], v[176:179], v[214:217], v[20:23]
	v_mfma_f32_16x16x32_bf16 v[16:19], v[184:187], v[214:217], v[16:19]
	v_mfma_f32_16x16x32_bf16 v[4:7], v[176:179], v[222:225], v[4:7]
	v_mfma_f32_16x16x32_bf16 v[0:3], v[184:187], v[222:225], v[0:3]
	s_setprio 0
	s_barrier
	s_add_i32 s50, s50, 2
	s_add_u32 s24, s24, 0x100
	s_addc_u32 s25, s25, 0
	s_add_u32 s44, s44, 0x100
	s_addc_u32 s45, s45, 0
	s_cmp_gt_u32 s50, 13
	s_cbranch_scc0 .LBB0_462
	s_and_b64 vcc, exec, s[14:15]
	s_cbranch_vccz .LBB0_465
	s_barrier

; #define PG8_STAGE(bufoff, gbase, voff) do { _Pragma("unroll") for (int _i = 0; _i < 2; ++_i) \
;         __builtin_amdgcn_global_load_lds((const unsigned*)((const char*)(gbase) + (voff)[_i]), (PG8_LAS unsigned*)(lds + (bufoff) + ldsw + _i * 8192), 16, 0, 0); } while (0)
; #define PG8_LDA(dst, b, h) do { _Pragma("unroll") for (int m = 0; m < 4; ++m) _Pragma("unroll") for (int k = 0; k < 2; ++k) dst[m][k] = *(const PG8_LAS bf16x8*)(lds + PG8_SA(b, h) + aoff + m * 2048 + k * 1024); } while (0)
; #define PG8_LDB(dst, b, h) do { _Pragma("unroll") for (int n = 0; n < 2; ++n) _Pragma("unroll") for (int k = 0; k < 2; ++k) dst[n][k] = *(const PG8_LAS bf16x8*)(lds + PG8_SB(b, h) + boff + n * 2048 + k * 1024); } while (0)
; #define PG8_MMA(ai, bj, At, Bt) do { __builtin_amdgcn_s_setprio(1); _Pragma("unroll") for (int m = 0; m < 4; ++m) _Pragma("unroll") for (int n = 0; n < 2; ++n) _Pragma("unroll") for (int k = 0; k < 2; ++k) \
;         acc[ai][bj][m][n] = __builtin_amdgcn_mfma_f32_16x16x32_bf16(Bt[n][k], At[m][k], acc[ai][bj][m][n], 0, 0, 0); __builtin_amdgcn_s_setprio(0); } while (0)
; #define PG8_WAIT_V(n) asm volatile("s_waitcnt vmcnt(" #n ")" ::: "memory")
; #define PG8_WAIT_L(n) asm volatile("s_waitcnt lgkmcnt(" #n ")" ::: "memory")
; #define PG8_BAR __builtin_amdgcn_s_barrier()
; template <class Epi, class Sched, bool ALIGN_EPI = false, bool SP2 = false>
; __device__ __forceinline__ void gemm_phase(PG8_LAS unsigned char* lds, const Gemm g, const Sched& S, const Epi& E) {
;     ...
;             const char* a1 = cA + (size_t)(t + 1) * kstep;
;             const char* a2 = last ? nA : cA + (size_t)(t + 2) * kstep; const char* b2 = last ? nB : cB + (size_t)(t + 2) * kstep;
;             const char* a3 = a2 + kstep; const char* b3 = b2 + kstep;
;             if (last && has_next) S.a_ready(nxt);
;             if constexpr (SP2) {
;             PG8_LDB(B0, 0, 0); PG8_LDB(B1, 0, 1); PG8_SCHED; PG8_LDA(At, 0, 0); PG8_STAGE(PG8_SA(1, 1), a1 + hstep, voffA);
;             PG8_WAIT_V(8); PG8_WAIT_L(0); PG8_BAR; PG8_MMA(0, 0, At, B0); PG8_MMA(0, 1, At, B1); PG8_BAR; PG8_SCHED;
;             PG8_LDA(At, 0, 1); PG8_STAGE(PG8_SB(0, 0), b2, voffB); PG8_STAGE(PG8_SB(0, 1), b2 + hstep, voffB); PG8_STAGE(PG8_SA(0, 0), a2, voffA);
;             PG8_WAIT_V(8); PG8_WAIT_L(0); PG8_BAR; PG8_MMA(1, 0, At, B0); PG8_MMA(1, 1, At, B1); PG8_BAR; PG8_SCHED;
.LBB0_501:
	ds_read_b128 v[144:147], v151
	ds_read_b128 v[154:157], v151 offset:1024
	ds_read_b128 v[158:161], v151 offset:2048
	ds_read_b128 v[162:165], v151 offset:3072
	ds_read_b128 v[166:169], v152
	ds_read_b128 v[170:173], v152 offset:1024
	ds_read_b128 v[174:177], v152 offset:2048
	ds_read_b128 v[178:181], v152 offset:3072
	s_add_u32 s28, s26, 0xfff00080
	s_addc_u32 s29, s27, -1
	s_cmp_eq_u32 s56, 60
	s_cselect_b32 s35, s19, s29
	s_cselect_b32 s34, s25, s28
	s_cselect_b32 s29, s17, s51
	s_cselect_b32 s28, s45, s50
	s_add_u32 vcc_lo, s28, 0x80
	s_addc_u32 vcc_hi, s29, 0
	s_add_u32 s100, s34, 0x80
	s_addc_u32 s101, s35, 0
	s_add_i32 m0, s1, 0xc000
	ds_read_b128 v[182:185], v153
	ds_read_b128 v[186:189], v153 offset:1024
	ds_read_b128 v[194:197], v153 offset:2048
	ds_read_b128 v[198:201], v153 offset:3072
	ds_read_b128 v[202:205], v153 offset:4096
	ds_read_b128 v[206:209], v153 offset:5120
	ds_read_b128 v[210:213], v153 offset:6144
	ds_read_b128 v[214:217], v153 offset:7168
	global_load_lds_dwordx4 v136, s[26:27]
	s_add_i32 m0, s1, 0xe000
	s_nop 0
	global_load_lds_dwordx4 v138, s[26:27]
	s_waitcnt vmcnt(8)
	s_waitcnt lgkmcnt(0)
	s_barrier
	s_setprio 1
	s_waitcnt lgkmcnt(0)
	v_mfma_f32_16x16x32_bf16 v[124:127], v[144:147], v[182:185], v[124:127]
	v_mfma_f32_16x16x32_bf16 v[120:123], v[158:161], v[182:185], v[120:123]
	v_mfma_f32_16x16x32_bf16 v[108:111], v[144:147], v[194:197], v[108:111]
	v_mfma_f32_16x16x32_bf16 v[104:107], v[158:161], v[194:197], v[104:107]
	v_mfma_f32_16x16x32_bf16 v[92:95], v[144:147], v[202:205], v[92:95]
	v_mfma_f32_16x16x32_bf16 v[88:91], v[158:161], v[202:205], v[88:91]
	v_mfma_f32_16x16x32_bf16 v[76:79], v[144:147], v[210:213], v[76:79]
	v_mfma_f32_16x16x32_bf16 v[72:75], v[158:161], v[210:213], v[72:75]
	v_mfma_f32_16x16x32_bf16 v[124:127], v[154:157], v[186:189], v[124:127]
	v_mfma_f32_16x16x32_bf16 v[120:123], v[162:165], v[186:189], v[120:123]
	v_mfma_f32_16x16x32_bf16 v[108:111], v[154:157], v[198:201], v[108:111]
	v_mfma_f32_16x16x32_bf16 v[104:107], v[162:165], v[198:201], v[104:107]
	v_mfma_f32_16x16x32_bf16 v[92:95], v[154:157], v[206:209], v[92:95]
	v_mfma_f32_16x16x32_bf16 v[88:91], v[162:165], v[206:209], v[88:91]
	v_mfma_f32_16x16x32_bf16 v[76:79], v[154:157], v[214:217], v[76:79]
	v_mfma_f32_16x16x32_bf16 v[72:75], v[162:165], v[214:217], v[72:75]
	s_setprio 0
	s_setprio 1
	v_mfma_f32_16x16x32_bf16 v[116:119], v[166:169], v[182:185], v[116:119]
	v_mfma_f32_16x16x32_bf16 v[112:115], v[174:177], v[182:185], v[112:115]
	v_mfma_f32_16x16x32_bf16 v[100:103], v[166:169], v[194:197], v[100:103]
	v_mfma_f32_16x16x32_bf16 v[96:99], v[174:177], v[194:197], v[96:99]
	v_mfma_f32_16x16x32_bf16 v[84:87], v[166:169], v[202:205], v[84:87]
	v_mfma_f32_16x16x32_bf16 v[80:83], v[174:177], v[202:205], v[80:83]
	v_mfma_f32_16x16x32_bf16 v[68:71], v[166:169], v[210:213], v[68:71]
	v_mfma_f32_16x16x32_bf16 v[64:67], v[174:177], v[210:213], v[64:67]
	v_mfma_f32_16x16x32_bf16 v[116:119], v[170:173], v[186:189], v[116:119]
	v_mfma_f32_16x16x32_bf16 v[112:115], v[178:181], v[186:189], v[112:115]
	v_mfma_f32_16x16x32_bf16 v[100:103], v[170:173], v[198:201], v[100:103]
	v_mfma_f32_16x16x32_bf16 v[96:99], v[178:181], v[198:201], v[96:99]
	v_mfma_f32_16x16x32_bf16 v[84:87], v[170:173], v[206:209], v[84:87]
	v_mfma_f32_16x16x32_bf16 v[80:83], v[178:181], v[206:209], v[80:83]
	v_mfma_f32_16x16x32_bf16 v[68:71], v[170:173], v[214:217], v[68:71]
	v_mfma_f32_16x16x32_bf16 v[64:67], v[178:181], v[214:217], v[64:67]
	s_setprio 0
	s_barrier
	s_add_i32 s57, s41, s0
	s_mov_b32 m0, s57
	ds_read_b128 v[182:185], v153 offset:16384
	ds_read_b128 v[186:189], v153 offset:17408
	ds_read_b128 v[194:197], v153 offset:18432
	ds_read_b128 v[198:201], v153 offset:19456
	ds_read_b128 v[202:205], v153 offset:20480
	ds_read_b128 v[206:209], v153 offset:21504
	ds_read_b128 v[210:213], v153 offset:22528
	ds_read_b128 v[214:217], v153 offset:23552
	global_load_lds_dwordx4 v130, s[28:29]
	s_add_i32 m0, s57, 0x2000
	s_add_u32 s58, s28, 0x100000
	s_addc_u32 s59, s29, 0
	s_add_i32 s57, s42, s0
	global_load_lds_dwordx4 v134, s[28:29]
	s_mov_b32 m0, s57
	s_nop 0
	global_load_lds_dwordx4 v130, s[58:59]
	s_add_i32 m0, s57, 0x2000
	s_nop 0
	global_load_lds_dwordx4 v134, s[58:59]
	s_mov_b32 m0, s1
	s_nop 0
	global_load_lds_dwordx4 v128, s[34:35]
	s_mov_b32 m0, s31
	s_nop 0
	global_load_lds_dwordx4 v132, s[34:35]
	s_waitcnt vmcnt(8)
	s_waitcnt lgkmcnt(0)
	s_barrier
	s_setprio 1
	s_waitcnt lgkmcnt(0)
	v_mfma_f32_16x16x32_bf16 v[60:63], v[144:147], v[182:185], v[60:63]
	v_mfma_f32_16x16x32_bf16 v[56:59], v[158:161], v[182:185], v[56:59]
	v_mfma_f32_16x16x32_bf16 v[44:47], v[144:147], v[194:197], v[44:47]
	v_mfma_f32_16x16x32_bf16 v[40:43], v[158:161], v[194:197], v[40:43]
	v_mfma_f32_16x16x32_bf16 v[28:31], v[144:147], v[202:205], v[28:31]
	v_mfma_f32_16x16x32_bf16 v[24:27], v[158:161], v[202:205], v[24:27]
	v_mfma_f32_16x16x32_bf16 v[12:15], v[144:147], v[210:213], v[12:15]
	v_mfma_f32_16x16x32_bf16 v[8:11], v[158:161], v[210:213], v[8:11]
	v_mfma_f32_16x16x32_bf16 v[60:63], v[154:157], v[186:189], v[60:63]
	v_mfma_f32_16x16x32_bf16 v[56:59], v[162:165], v[186:189], v[56:59]
	v_mfma_f32_16x16x32_bf16 v[44:47], v[154:157], v[198:201], v[44:47]
	v_mfma_f32_16x16x32_bf16 v[40:43], v[162:165], v[198:201], v[40:43]
	v_mfma_f32_16x16x32_bf16 v[28:31], v[154:157], v[206:209], v[28:31]
	v_mfma_f32_16x16x32_bf16 v[24:27], v[162:165], v[206:209], v[24:27]
	v_mfma_f32_16x16x32_bf16 v[12:15], v[154:157], v[214:217], v[12:15]
	v_mfma_f32_16x16x32_bf16 v[8:11], v[162:165], v[214:217], v[8:11]
	s_setprio 0
	s_setprio 1
	v_mfma_f32_16x16x32_bf16 v[52:55], v[166:169], v[182:185], v[52:55]
	v_mfma_f32_16x16x32_bf16 v[48:51], v[174:177], v[182:185], v[48:51]
	v_mfma_f32_16x16x32_bf16 v[36:39], v[166:169], v[194:197], v[36:39]
	v_mfma_f32_16x16x32_bf16 v[32:35], v[174:177], v[194:197], v[32:35]
	v_mfma_f32_16x16x32_bf16 v[20:23], v[166:169], v[202:205], v[20:23]
	v_mfma_f32_16x16x32_bf16 v[16:19], v[174:177], v[202:205], v[16:19]
	v_mfma_f32_16x16x32_bf16 v[4:7], v[166:169], v[210:213], v[4:7]
	v_mfma_f32_16x16x32_bf16 v[0:3], v[174:177], v[210:213], v[0:3]
	v_mfma_f32_16x16x32_bf16 v[52:55], v[170:173], v[186:189], v[52:55]
	v_mfma_f32_16x16x32_bf16 v[48:51], v[178:181], v[186:189], v[48:51]
	v_mfma_f32_16x16x32_bf16 v[36:39], v[170:173], v[198:201], v[36:39]
	v_mfma_f32_16x16x32_bf16 v[32:35], v[178:181], v[198:201], v[32:35]
	v_mfma_f32_16x16x32_bf16 v[20:23], v[170:173], v[206:209], v[20:23]
	v_mfma_f32_16x16x32_bf16 v[16:19], v[178:181], v[206:209], v[16:19]
	v_mfma_f32_16x16x32_bf16 v[4:7], v[170:173], v[214:217], v[4:7]
	v_mfma_f32_16x16x32_bf16 v[0:3], v[178:181], v[214:217], v[0:3]
	s_setprio 0
	s_barrier
; #define PG8_STAGE(bufoff, gbase, voff) do { _Pragma("unroll") for (int _i = 0; _i < 2; ++_i) \
;         __builtin_amdgcn_global_load_lds((const unsigned*)((const char*)(gbase) + (voff)[_i]), (PG8_LAS unsigned*)(lds + (bufoff) + ldsw + _i * 8192), 16, 0, 0); } while (0)
; #define PG8_LDA(dst, b, h) do { _Pragma("unroll") for (int m = 0; m < 4; ++m) _Pragma("unroll") for (int k = 0; k < 2; ++k) dst[m][k] = *(const PG8_LAS bf16x8*)(lds + PG8_SA(b, h) + aoff + m * 2048 + k * 1024); } while (0)
; #define PG8_LDB(dst, b, h) do { _Pragma("unroll") for (int n = 0; n < 2; ++n) _Pragma("unroll") for (int k = 0; k < 2; ++k) dst[n][k] = *(const PG8_LAS bf16x8*)(lds + PG8_SB(b, h) + boff + n * 2048 + k * 1024); } while (0)
; #define PG8_MMA(ai, bj, At, Bt) do { __builtin_amdgcn_s_setprio(1); _Pragma("unroll") for (int m = 0; m < 4; ++m) _Pragma("unroll") for (int n = 0; n < 2; ++n) _Pragma("unroll") for (int k = 0; k < 2; ++k) \
;         acc[ai][bj][m][n] = __builtin_amdgcn_mfma_f32_16x16x32_bf16(Bt[n][k], At[m][k], acc[ai][bj][m][n], 0, 0, 0); __builtin_amdgcn_s_setprio(0); } while (0)
; #define PG8_WAIT_V(n) asm volatile("s_waitcnt vmcnt(" #n ")" ::: "memory")
; #define PG8_WAIT_L(n) asm volatile("s_waitcnt lgkmcnt(" #n ")" ::: "memory")
; #define PG8_BAR __builtin_amdgcn_s_barrier()
; #define PG8_SCHED __builtin_amdgcn_sched_barrier(0)
; template <class Epi, class Sched, bool ALIGN_EPI = false, bool SP2 = false>
; __device__ __forceinline__ void gemm_phase(PG8_LAS unsigned char* lds, const Gemm g, const Sched& S, const Epi& E) {
;     ...
;             PG8_LDB(B0, 1, 0); PG8_LDB(B1, 1, 1); PG8_SCHED; PG8_LDA(At, 1, 0); PG8_STAGE(PG8_SA(0, 1), a2 + hstep, voffA);
;             PG8_WAIT_V(8); PG8_WAIT_L(0); PG8_BAR; PG8_MMA(0, 0, At, B0); PG8_MMA(0, 1, At, B1); PG8_BAR; PG8_SCHED;
;             PG8_LDA(At, 1, 1); PG8_STAGE(PG8_SB(1, 0), b3, voffB); PG8_STAGE(PG8_SB(1, 1), b3 + hstep, voffB); PG8_STAGE(PG8_SA(1, 0), a3, voffA);
;             PG8_WAIT_V(8); PG8_WAIT_L(0); PG8_BAR; PG8_MMA(1, 0, At, B0); PG8_MMA(1, 1, At, B1); PG8_BAR; PG8_SCHED;
	s_add_i32 s57, 0, 0x18000
	s_add_i32 s58, 0, 0x1c000
	v_add_u32_e32 v162, s57, v149
	v_add_u32_e32 v178, s58, v149
	ds_read_b128 v[144:147], v162
	ds_read_b128 v[154:157], v162 offset:1024
	ds_read_b128 v[158:161], v162 offset:2048
	ds_read_b128 v[162:165], v162 offset:3072
	ds_read_b128 v[166:169], v178
	ds_read_b128 v[170:173], v178 offset:1024
	ds_read_b128 v[174:177], v178 offset:2048
	ds_read_b128 v[178:181], v178 offset:3072
	s_add_u32 s34, s34, 0x100000
	s_addc_u32 s35, s35, 0
	s_mov_b32 m0, s36
	ds_read_b128 v[182:185], v153 offset:32768
	ds_read_b128 v[186:189], v153 offset:33792
	ds_read_b128 v[194:197], v153 offset:34816
	ds_read_b128 v[198:201], v153 offset:35840
	ds_read_b128 v[202:205], v153 offset:36864
	ds_read_b128 v[206:209], v153 offset:37888
	ds_read_b128 v[210:213], v153 offset:38912
	ds_read_b128 v[214:217], v153 offset:39936
	global_load_lds_dwordx4 v128, s[34:35]
	s_mov_b32 m0, s37
	s_nop 0
	global_load_lds_dwordx4 v132, s[34:35]
	s_waitcnt vmcnt(8)
	s_waitcnt lgkmcnt(0)
	s_barrier
	s_setprio 1
	s_waitcnt lgkmcnt(0)
	v_mfma_f32_16x16x32_bf16 v[124:127], v[144:147], v[182:185], v[124:127]
	v_mfma_f32_16x16x32_bf16 v[120:123], v[158:161], v[182:185], v[120:123]
	v_mfma_f32_16x16x32_bf16 v[108:111], v[144:147], v[194:197], v[108:111]
	v_mfma_f32_16x16x32_bf16 v[104:107], v[158:161], v[194:197], v[104:107]
	v_mfma_f32_16x16x32_bf16 v[92:95], v[144:147], v[202:205], v[92:95]
	v_mfma_f32_16x16x32_bf16 v[88:91], v[158:161], v[202:205], v[88:91]
	v_mfma_f32_16x16x32_bf16 v[76:79], v[144:147], v[210:213], v[76:79]
	v_mfma_f32_16x16x32_bf16 v[72:75], v[158:161], v[210:213], v[72:75]
	v_mfma_f32_16x16x32_bf16 v[124:127], v[154:157], v[186:189], v[124:127]
	v_mfma_f32_16x16x32_bf16 v[120:123], v[162:165], v[186:189], v[120:123]
	v_mfma_f32_16x16x32_bf16 v[108:111], v[154:157], v[198:201], v[108:111]
	v_mfma_f32_16x16x32_bf16 v[104:107], v[162:165], v[198:201], v[104:107]
	v_mfma_f32_16x16x32_bf16 v[92:95], v[154:157], v[206:209], v[92:95]
	v_mfma_f32_16x16x32_bf16 v[88:91], v[162:165], v[206:209], v[88:91]
	v_mfma_f32_16x16x32_bf16 v[76:79], v[154:157], v[214:217], v[76:79]
	v_mfma_f32_16x16x32_bf16 v[72:75], v[162:165], v[214:217], v[72:75]
	s_setprio 0
	s_setprio 1
	v_mfma_f32_16x16x32_bf16 v[116:119], v[166:169], v[182:185], v[116:119]
	v_mfma_f32_16x16x32_bf16 v[112:115], v[174:177], v[182:185], v[112:115]
	v_mfma_f32_16x16x32_bf16 v[100:103], v[166:169], v[194:197], v[100:103]
	v_mfma_f32_16x16x32_bf16 v[96:99], v[174:177], v[194:197], v[96:99]
	v_mfma_f32_16x16x32_bf16 v[84:87], v[166:169], v[202:205], v[84:87]
	v_mfma_f32_16x16x32_bf16 v[80:83], v[174:177], v[202:205], v[80:83]
	v_mfma_f32_16x16x32_bf16 v[68:71], v[166:169], v[210:213], v[68:71]
	v_mfma_f32_16x16x32_bf16 v[64:67], v[174:177], v[210:213], v[64:67]
	v_mfma_f32_16x16x32_bf16 v[116:119], v[170:173], v[186:189], v[116:119]
	v_mfma_f32_16x16x32_bf16 v[112:115], v[178:181], v[186:189], v[112:115]
	v_mfma_f32_16x16x32_bf16 v[100:103], v[170:173], v[198:201], v[100:103]
	v_mfma_f32_16x16x32_bf16 v[96:99], v[178:181], v[198:201], v[96:99]
	v_mfma_f32_16x16x32_bf16 v[84:87], v[170:173], v[206:209], v[84:87]
	v_mfma_f32_16x16x32_bf16 v[80:83], v[178:181], v[206:209], v[80:83]
	v_mfma_f32_16x16x32_bf16 v[68:71], v[170:173], v[214:217], v[68:71]
	v_mfma_f32_16x16x32_bf16 v[64:67], v[178:181], v[214:217], v[64:67]
	s_setprio 0
	s_barrier
	s_add_i32 s34, s57, s0
	s_mov_b32 m0, s34
	ds_read_b128 v[182:185], v153 offset:49152
	ds_read_b128 v[186:189], v153 offset:50176
	ds_read_b128 v[194:197], v153 offset:51200
	ds_read_b128 v[198:201], v153 offset:52224
	ds_read_b128 v[202:205], v153 offset:53248
	ds_read_b128 v[206:209], v153 offset:54272
	ds_read_b128 v[210:213], v153 offset:55296
	ds_read_b128 v[214:217], v153 offset:56320
	global_load_lds_dwordx4 v130, vcc
	s_add_i32 m0, s34, 0x2000
	s_add_u32 s28, s28, 0x100080
	s_addc_u32 s29, s29, 0
	s_add_i32 s34, s58, s0
	global_load_lds_dwordx4 v134, vcc
	s_mov_b32 m0, s34
	s_nop 0
	global_load_lds_dwordx4 v130, s[28:29]
	s_add_i32 m0, s34, 0x2000
	s_nop 0
	global_load_lds_dwordx4 v134, s[28:29]
	s_mov_b32 m0, s39
	s_nop 0
	global_load_lds_dwordx4 v128, s[100:101]
	s_mov_b32 m0, s40
	s_nop 0
	global_load_lds_dwordx4 v132, s[100:101]
	s_waitcnt vmcnt(8)
	s_waitcnt lgkmcnt(0)
	s_barrier
	s_setprio 1
	s_waitcnt lgkmcnt(0)
	v_mfma_f32_16x16x32_bf16 v[60:63], v[144:147], v[182:185], v[60:63]
	v_mfma_f32_16x16x32_bf16 v[56:59], v[158:161], v[182:185], v[56:59]
	v_mfma_f32_16x16x32_bf16 v[44:47], v[144:147], v[194:197], v[44:47]
	v_mfma_f32_16x16x32_bf16 v[40:43], v[158:161], v[194:197], v[40:43]
	v_mfma_f32_16x16x32_bf16 v[28:31], v[144:147], v[202:205], v[28:31]
	v_mfma_f32_16x16x32_bf16 v[24:27], v[158:161], v[202:205], v[24:27]
	v_mfma_f32_16x16x32_bf16 v[12:15], v[144:147], v[210:213], v[12:15]
	v_mfma_f32_16x16x32_bf16 v[8:11], v[158:161], v[210:213], v[8:11]
	v_mfma_f32_16x16x32_bf16 v[60:63], v[154:157], v[186:189], v[60:63]
	v_mfma_f32_16x16x32_bf16 v[56:59], v[162:165], v[186:189], v[56:59]
	v_mfma_f32_16x16x32_bf16 v[44:47], v[154:157], v[198:201], v[44:47]
	v_mfma_f32_16x16x32_bf16 v[40:43], v[162:165], v[198:201], v[40:43]
	v_mfma_f32_16x16x32_bf16 v[28:31], v[154:157], v[206:209], v[28:31]
	v_mfma_f32_16x16x32_bf16 v[24:27], v[162:165], v[206:209], v[24:27]
	v_mfma_f32_16x16x32_bf16 v[12:15], v[154:157], v[214:217], v[12:15]
	v_mfma_f32_16x16x32_bf16 v[8:11], v[162:165], v[214:217], v[8:11]
	s_setprio 0
	s_setprio 1
	v_mfma_f32_16x16x32_bf16 v[52:55], v[166:169], v[182:185], v[52:55]
	v_mfma_f32_16x16x32_bf16 v[48:51], v[174:177], v[182:185], v[48:51]
	v_mfma_f32_16x16x32_bf16 v[36:39], v[166:169], v[194:197], v[36:39]
	v_mfma_f32_16x16x32_bf16 v[32:35], v[174:177], v[194:197], v[32:35]
	v_mfma_f32_16x16x32_bf16 v[20:23], v[166:169], v[202:205], v[20:23]
	v_mfma_f32_16x16x32_bf16 v[16:19], v[174:177], v[202:205], v[16:19]
	v_mfma_f32_16x16x32_bf16 v[4:7], v[166:169], v[210:213], v[4:7]
	v_mfma_f32_16x16x32_bf16 v[0:3], v[174:177], v[210:213], v[0:3]
	v_mfma_f32_16x16x32_bf16 v[52:55], v[170:173], v[186:189], v[52:55]
	v_mfma_f32_16x16x32_bf16 v[48:51], v[178:181], v[186:189], v[48:51]
	v_mfma_f32_16x16x32_bf16 v[36:39], v[170:173], v[198:201], v[36:39]
	v_mfma_f32_16x16x32_bf16 v[32:35], v[178:181], v[198:201], v[32:35]
	v_mfma_f32_16x16x32_bf16 v[20:23], v[170:173], v[206:209], v[20:23]
	v_mfma_f32_16x16x32_bf16 v[16:19], v[178:181], v[206:209], v[16:19]
	v_mfma_f32_16x16x32_bf16 v[4:7], v[170:173], v[214:217], v[4:7]
	v_mfma_f32_16x16x32_bf16 v[0:3], v[178:181], v[214:217], v[0:3]
	s_setprio 0
	s_barrier
	s_add_i32 s56, s56, 2
	s_add_u32 s26, s26, 0x100
	s_addc_u32 s27, s27, 0
	s_add_u32 s50, s50, 0x100
	s_addc_u32 s51, s51, 0
	s_cmp_gt_u32 s56, 61
	s_cbranch_scc0 .LBB0_501
	s_and_b64 vcc, exec, s[14:15]
	s_cbranch_vccz .LBB0_504
	s_barrier
